# SSM pass A rewritten by hand: plain f32 v_fma/v_fmac instead of SLP-packed VOP3P ops and register shuffles, 4-deep U prefetch, reduction of sub-block j-1 overlapped with MFMAs of j
# speedup vs baseline: 1.0207x; 1.0117x over previous
.LBB0_1308:
	s_or_b64 exec, exec, s[2:3]
	v_readlane_b32 s0, v255, 3
	v_readlane_b32 s1, v255, 4
	s_waitcnt lgkmcnt(0)
	s_barrier
	s_load_dwordx4 s[52:55], s[0:1], 0xc8
	s_load_dwordx2 s[2:3], s[0:1], 0xa0
	s_load_dwordx4 s[56:59], s[0:1], 0x28
	s_load_dwordx4 s[60:63], s[0:1], 0x90
	v_readlane_b32 s0, v255, 18
	s_waitcnt lgkmcnt(0)
	s_add_u32 s64, s54, 0x5200000
	s_addc_u32 s65, s55, 0
	v_mov_b32_e32 v2, v0
	s_add_u32 s66, s54, 0x30000
	v_readlane_b32 s1, v255, 19
	s_addc_u32 s67, s55, 0
	s_andn2_b64 vcc, exec, s[0:1]
	v_readfirstlane_b32 s0, v2
	s_cbranch_vccnz .LBB0_1315
	s_cmp_eq_u32 s97, 0x100
	s_cbranch_scc0 .Lpa_compiled
	v_readlane_b32 s6, v255, 7
	v_readlane_b32 s7, v255, 2
	s_nop 0
	s_lshr_b32 s7, s7, 6
	s_and_b32 s8, s6, 15
	s_lshl_b32 s8, s8, 3
	s_add_i32 s8, s8, s7
	s_bfe_u32 s9, s6, 0x30004
	s_lshr_b32 s10, s6, 7
	s_lshl_b32 s11, s8, 9
	s_add_u32 s34, s54, 0x30000
	s_addc_u32 s35, s55, 0
	s_add_u32 s34, s34, s11
	s_addc_u32 s35, s35, 0
	s_lshl_b32 s11, s8, 12
	s_add_u32 s36, s54, 0x140000
	s_addc_u32 s37, s55, 0
	s_add_u32 s36, s36, s11
	s_addc_u32 s37, s37, 0
	s_lshl_b32 s11, s10, 24
	s_lshl_b32 s14, s9, 21
	s_add_i32 s11, s11, s14
	s_lshl_b32 s14, s8, 5
	s_add_i32 s11, s11, s14
	s_add_u32 s32, s54, 0x5200000
	s_addc_u32 s33, s55, 0
	s_add_u32 s32, s32, s11
	s_addc_u32 s33, s33, 0
	s_lshl_b32 s11, s10, 7
	s_add_i32 s11, s11, s8
	s_lshl_b32 s11, s11, 5
	s_lshl_b32 s14, s9, 2
	s_add_i32 s11, s11, s14
	s_lshl_b32 s11, s11, 9
	s_add_u32 s38, s54, 0x600000
	s_addc_u32 s39, s55, 0
	s_add_u32 s38, s38, s11
	s_addc_u32 s39, s39, 0
	s_mov_b32 s12, -1
	s_mov_b32 s13, 0
	v_and_b32_e32 v219, 63, v0
	v_and_b32_e32 v220, 31, v219
	v_lshrrev_b32_e32 v221, 5, v219
	v_xor_b32_e32 v208, 32, v219
	v_lshlrev_b32_e32 v208, 2, v208
	v_lshlrev_b32_e32 v209, 2, v220
	v_lshlrev_b32_e32 v210, 12, v220
	v_lshl_add_u32 v210, v221, 4, v210
	v_lshlrev_b32_e32 v222, 3, v220
	v_lshlrev_b32_e32 v223, 4, v219
	v_cmp_lt_u32_e64 s[40:41], 31, v219
	global_load_dwordx2 v[228:229], v222, s[34:35]
	global_load_dwordx2 v[244:245], v222, s[34:35] offset:256
	global_load_dwordx4 v[6:9], v223, s[36:37] offset:0
	global_load_dwordx4 v[10:13], v223, s[36:37] offset:1024
	global_load_dwordx4 v[14:17], v223, s[36:37] offset:2048
	global_load_dwordx4 v[18:21], v223, s[36:37] offset:3072
	s_add_u32 s42, s32, 0x0
	s_addc_u32 s43, s33, 0
	global_load_dwordx4 v[192:195], v210, s[42:43]
	s_add_u32 s42, s32, 0x20000
	s_addc_u32 s43, s33, 0
	global_load_dwordx4 v[196:199], v210, s[42:43]
	s_add_u32 s42, s32, 0x40000
	s_addc_u32 s43, s33, 0
	global_load_dwordx4 v[200:203], v210, s[42:43]
	s_add_u32 s42, s32, 0x60000
	s_addc_u32 s43, s33, 0
	global_load_dwordx4 v[204:207], v210, s[42:43]
	s_waitcnt vmcnt(9)
	v_mul_f32_e32 v242, v229, v229
	v_fma_f32 v230, v228, v228, -v242
	v_mul_f32_e32 v242, v229, v228
	v_fma_f32 v231, v228, v229, v242
	v_mul_f32_e32 v242, v231, v229
	v_fma_f32 v232, v230, v228, -v242
	v_mul_f32_e32 v242, v231, v228
	v_fma_f32 v233, v230, v229, v242
	v_mul_f32_e32 v242, v231, v231
	v_fma_f32 v234, v230, v230, -v242
	v_mul_f32_e32 v242, v231, v230
	v_fma_f32 v235, v230, v231, v242
	v_mul_f32_e32 v242, v235, v235
	v_fma_f32 v236, v234, v234, -v242
	v_mul_f32_e32 v242, v235, v234
	v_fma_f32 v237, v234, v235, v242
	v_mul_f32_e32 v242, v237, v237
	v_fma_f32 v238, v236, v236, -v242
	v_mul_f32_e32 v242, v237, v236
	v_fma_f32 v239, v236, v237, v242
	v_mul_f32_e32 v242, v239, v239
	v_fma_f32 v167, v238, v238, -v242
	v_mul_f32_e32 v242, v239, v238
	v_fma_f32 v168, v238, v239, v242
	v_cndmask_b32_e64 v240, v234, 1.0, s[40:41]
	v_cndmask_b32_e64 v241, v235, 0, s[40:41]
	v_mov_b32_e32 v101, v240
	v_mov_b32_e32 v117, v241
	v_mul_f32_e32 v242, v241, v229
	v_fma_f32 v100, v240, v228, -v242
	v_mul_f32_e32 v242, v241, v228
	v_fma_f32 v116, v240, v229, v242
	v_mul_f32_e32 v242, v241, v231
	v_fma_f32 v99, v240, v230, -v242
	v_mul_f32_e32 v242, v241, v230
	v_fma_f32 v115, v240, v231, v242
	v_mul_f32_e32 v242, v241, v233
	v_fma_f32 v98, v240, v232, -v242
	v_mul_f32_e32 v242, v241, v232
	v_fma_f32 v114, v240, v233, v242
	v_mul_f32_e32 v242, v117, v237
	v_fma_f32 v97, v101, v236, -v242
	v_mul_f32_e32 v242, v117, v236
	v_fma_f32 v113, v101, v237, v242
	v_mul_f32_e32 v242, v116, v237
	v_fma_f32 v96, v100, v236, -v242
	v_mul_f32_e32 v242, v116, v236
	v_fma_f32 v112, v100, v237, v242
	v_mul_f32_e32 v242, v115, v237
	v_fma_f32 v95, v99, v236, -v242
	v_mul_f32_e32 v242, v115, v236
	v_fma_f32 v111, v99, v237, v242
	v_mul_f32_e32 v242, v114, v237
	v_fma_f32 v94, v98, v236, -v242
	v_mul_f32_e32 v242, v114, v236
	v_fma_f32 v110, v98, v237, v242
	v_mul_f32_e32 v242, v113, v237
	v_fma_f32 v93, v97, v236, -v242
	v_mul_f32_e32 v242, v113, v236
	v_fma_f32 v109, v97, v237, v242
	v_mul_f32_e32 v242, v112, v237
	v_fma_f32 v92, v96, v236, -v242
	v_mul_f32_e32 v242, v112, v236
	v_fma_f32 v108, v96, v237, v242
	v_mul_f32_e32 v242, v111, v237
	v_fma_f32 v91, v95, v236, -v242
	v_mul_f32_e32 v242, v111, v236
	v_fma_f32 v107, v95, v237, v242
	v_mul_f32_e32 v242, v110, v237
	v_fma_f32 v90, v94, v236, -v242
	v_mul_f32_e32 v242, v110, v236
	v_fma_f32 v106, v94, v237, v242
	v_mul_f32_e32 v242, v109, v237
	v_fma_f32 v89, v93, v236, -v242
	v_mul_f32_e32 v242, v109, v236
	v_fma_f32 v105, v93, v237, v242
	v_mul_f32_e32 v242, v108, v237
	v_fma_f32 v88, v92, v236, -v242
	v_mul_f32_e32 v242, v108, v236
	v_fma_f32 v104, v92, v237, v242
	v_mul_f32_e32 v242, v107, v237
	v_fma_f32 v87, v91, v236, -v242
	v_mul_f32_e32 v242, v107, v236
	v_fma_f32 v103, v91, v237, v242
	v_mul_f32_e32 v242, v106, v237
	v_fma_f32 v86, v90, v236, -v242
	v_mul_f32_e32 v242, v106, v236
	v_fma_f32 v102, v90, v237, v242
	s_waitcnt vmcnt(8)
	v_mul_f32_e32 v242, v245, v245
	v_fma_f32 v230, v244, v244, -v242
	v_mul_f32_e32 v242, v245, v244
	v_fma_f32 v231, v244, v245, v242
	v_mul_f32_e32 v242, v231, v245
	v_fma_f32 v232, v230, v244, -v242
	v_mul_f32_e32 v242, v231, v244
	v_fma_f32 v233, v230, v245, v242
	v_mul_f32_e32 v242, v231, v231
	v_fma_f32 v234, v230, v230, -v242
	v_mul_f32_e32 v242, v231, v230
	v_fma_f32 v235, v230, v231, v242
	v_mul_f32_e32 v242, v235, v235
	v_fma_f32 v236, v234, v234, -v242
	v_mul_f32_e32 v242, v235, v234
	v_fma_f32 v237, v234, v235, v242
	v_mul_f32_e32 v242, v237, v237
	v_fma_f32 v238, v236, v236, -v242
	v_mul_f32_e32 v242, v237, v236
	v_fma_f32 v239, v236, v237, v242
	v_mul_f32_e32 v242, v239, v239
	v_fma_f32 v169, v238, v238, -v242
	v_mul_f32_e32 v242, v239, v238
	v_fma_f32 v170, v238, v239, v242
	v_cndmask_b32_e64 v240, v234, 1.0, s[40:41]
	v_cndmask_b32_e64 v241, v235, 0, s[40:41]
	v_mov_b32_e32 v133, v240
	v_mov_b32_e32 v149, v241
	v_mul_f32_e32 v242, v241, v245
	v_fma_f32 v132, v240, v244, -v242
	v_mul_f32_e32 v242, v241, v244
	v_fma_f32 v148, v240, v245, v242
	v_mul_f32_e32 v242, v241, v231
	v_fma_f32 v131, v240, v230, -v242
	v_mul_f32_e32 v242, v241, v230
	v_fma_f32 v147, v240, v231, v242
	v_mul_f32_e32 v242, v241, v233
	v_fma_f32 v130, v240, v232, -v242
	v_mul_f32_e32 v242, v241, v232
	v_fma_f32 v146, v240, v233, v242
	v_mul_f32_e32 v242, v149, v237
	v_fma_f32 v129, v133, v236, -v242
	v_mul_f32_e32 v242, v149, v236
	v_fma_f32 v145, v133, v237, v242
	v_mul_f32_e32 v242, v148, v237
	v_fma_f32 v128, v132, v236, -v242
	v_mul_f32_e32 v242, v148, v236
	v_fma_f32 v144, v132, v237, v242
	v_mul_f32_e32 v242, v147, v237
	v_fma_f32 v127, v131, v236, -v242
	v_mul_f32_e32 v242, v147, v236
	v_fma_f32 v143, v131, v237, v242
	v_mul_f32_e32 v242, v146, v237
	v_fma_f32 v126, v130, v236, -v242
	v_mul_f32_e32 v242, v146, v236
	v_fma_f32 v142, v130, v237, v242
	v_mul_f32_e32 v242, v145, v237
	v_fma_f32 v125, v129, v236, -v242
	v_mul_f32_e32 v242, v145, v236
	v_fma_f32 v141, v129, v237, v242
	v_mul_f32_e32 v242, v144, v237
	v_fma_f32 v124, v128, v236, -v242
	v_mul_f32_e32 v242, v144, v236
	v_fma_f32 v140, v128, v237, v242
	v_mul_f32_e32 v242, v143, v237
	v_fma_f32 v123, v127, v236, -v242
	v_mul_f32_e32 v242, v143, v236
	v_fma_f32 v139, v127, v237, v242
	v_mul_f32_e32 v242, v142, v237
	v_fma_f32 v122, v126, v236, -v242
	v_mul_f32_e32 v242, v142, v236
	v_fma_f32 v138, v126, v237, v242
	v_mul_f32_e32 v242, v141, v237
	v_fma_f32 v121, v125, v236, -v242
	v_mul_f32_e32 v242, v141, v236
	v_fma_f32 v137, v125, v237, v242
	v_mul_f32_e32 v242, v140, v237
	v_fma_f32 v120, v124, v236, -v242
	v_mul_f32_e32 v242, v140, v236
	v_fma_f32 v136, v124, v237, v242
	v_mul_f32_e32 v242, v139, v237
	v_fma_f32 v119, v123, v236, -v242
	v_mul_f32_e32 v242, v139, v236
	v_fma_f32 v135, v123, v237, v242
	v_mul_f32_e32 v242, v138, v237
	v_fma_f32 v118, v122, v236, -v242
	v_mul_f32_e32 v242, v138, v236
	v_fma_f32 v134, v122, v237, v242
	v_mov_b32_e32 v171, 0
	v_mov_b32_e32 v172, 0
	v_mov_b32_e32 v173, 0
	v_mov_b32_e32 v174, 0
	s_waitcnt vmcnt(3)
	v_mfma_f32_32x32x16_bf16 v[22:37], v[192:195], v[6:9], 0
	v_mfma_f32_32x32x16_bf16 v[54:69], v[192:195], v[14:17], 0
	v_mfma_f32_32x32x16_bf16 v[38:53], v[192:195], v[10:13], 0
	v_mfma_f32_32x32x16_bf16 v[70:85], v[192:195], v[18:21], 0
	s_add_u32 s42, s32, 0x80000
	s_addc_u32 s43, s33, 0
	global_load_dwordx4 v[192:195], v210, s[42:43]
	s_nop 7
	s_nop 3
	v_mul_f32_e32 v175, v86, v22
	v_mul_f32_e32 v179, v86, v54
	v_fma_f32 v175, -v102, v54, v175
	v_fmac_f32_e32 v179, v102, v22
	v_mul_f32_e32 v176, v87, v23
	v_mul_f32_e32 v180, v87, v55
	v_fma_f32 v176, -v103, v55, v176
	v_fmac_f32_e32 v180, v103, v23
	v_mul_f32_e32 v177, v88, v24
	v_mul_f32_e32 v181, v88, v56
	v_fma_f32 v177, -v104, v56, v177
	v_fmac_f32_e32 v181, v104, v24
	v_mul_f32_e32 v178, v89, v25
	v_mul_f32_e32 v182, v89, v57
	v_fma_f32 v178, -v105, v57, v178
	v_fmac_f32_e32 v182, v105, v25
	v_fmac_f32_e32 v175, v90, v26
	v_fmac_f32_e32 v179, v90, v58
	v_fma_f32 v175, -v106, v58, v175
	v_fmac_f32_e32 v179, v106, v26
	v_fmac_f32_e32 v176, v91, v27
	v_fmac_f32_e32 v180, v91, v59
	v_fma_f32 v176, -v107, v59, v176
	v_fmac_f32_e32 v180, v107, v27
	v_fmac_f32_e32 v177, v92, v28
	v_fmac_f32_e32 v181, v92, v60
	v_fma_f32 v177, -v108, v60, v177
	v_fmac_f32_e32 v181, v108, v28
	v_fmac_f32_e32 v178, v93, v29
	v_fmac_f32_e32 v182, v93, v61
	v_fma_f32 v178, -v109, v61, v178
	v_fmac_f32_e32 v182, v109, v29
	v_fmac_f32_e32 v175, v94, v30
	v_fmac_f32_e32 v179, v94, v62
	v_fma_f32 v175, -v110, v62, v175
	v_fmac_f32_e32 v179, v110, v30
	v_fmac_f32_e32 v176, v95, v31
	v_fmac_f32_e32 v180, v95, v63
	v_fma_f32 v176, -v111, v63, v176
	v_fmac_f32_e32 v180, v111, v31
	v_fmac_f32_e32 v177, v96, v32
	v_fmac_f32_e32 v181, v96, v64
	v_fma_f32 v177, -v112, v64, v177
	v_fmac_f32_e32 v181, v112, v32
	v_fmac_f32_e32 v178, v97, v33
	v_fmac_f32_e32 v182, v97, v65
	v_fma_f32 v178, -v113, v65, v178
	v_fmac_f32_e32 v182, v113, v33
	v_fmac_f32_e32 v175, v98, v34
	v_fmac_f32_e32 v179, v98, v66
	v_fma_f32 v175, -v114, v66, v175
	v_fmac_f32_e32 v179, v114, v34
	v_fmac_f32_e32 v176, v99, v35
	v_fmac_f32_e32 v180, v99, v67
	v_fma_f32 v176, -v115, v67, v176
	v_fmac_f32_e32 v180, v115, v35
	v_fmac_f32_e32 v177, v100, v36
	v_fmac_f32_e32 v181, v100, v68
	v_fma_f32 v177, -v116, v68, v177
	v_fmac_f32_e32 v181, v116, v36
	v_fmac_f32_e32 v178, v101, v37
	v_fmac_f32_e32 v182, v101, v69
	v_fma_f32 v178, -v117, v69, v178
	v_fmac_f32_e32 v182, v117, v37
	v_mul_f32_e32 v183, v118, v38
	v_mul_f32_e32 v187, v118, v70
	v_fma_f32 v183, -v134, v70, v183
	v_fmac_f32_e32 v187, v134, v38
	v_mul_f32_e32 v184, v119, v39
	v_mul_f32_e32 v188, v119, v71
	v_fma_f32 v184, -v135, v71, v184
	v_fmac_f32_e32 v188, v135, v39
	v_mul_f32_e32 v185, v120, v40
	v_mul_f32_e32 v189, v120, v72
	v_fma_f32 v185, -v136, v72, v185
	v_fmac_f32_e32 v189, v136, v40
	v_mul_f32_e32 v186, v121, v41
	v_mul_f32_e32 v190, v121, v73
	v_fma_f32 v186, -v137, v73, v186
	v_fmac_f32_e32 v190, v137, v41
	v_fmac_f32_e32 v183, v122, v42
	v_fmac_f32_e32 v187, v122, v74
	v_fma_f32 v183, -v138, v74, v183
	v_fmac_f32_e32 v187, v138, v42
	v_fmac_f32_e32 v184, v123, v43
	v_fmac_f32_e32 v188, v123, v75
	v_fma_f32 v184, -v139, v75, v184
	v_fmac_f32_e32 v188, v139, v43
	v_fmac_f32_e32 v185, v124, v44
	v_fmac_f32_e32 v189, v124, v76
	v_fma_f32 v185, -v140, v76, v185
	v_fmac_f32_e32 v189, v140, v44
	v_fmac_f32_e32 v186, v125, v45
	v_fmac_f32_e32 v190, v125, v77
	v_fma_f32 v186, -v141, v77, v186
	v_fmac_f32_e32 v190, v141, v45
	v_fmac_f32_e32 v183, v126, v46
	v_fmac_f32_e32 v187, v126, v78
	v_fma_f32 v183, -v142, v78, v183
	v_fmac_f32_e32 v187, v142, v46
	v_fmac_f32_e32 v184, v127, v47
	v_fmac_f32_e32 v188, v127, v79
	v_fma_f32 v184, -v143, v79, v184
	v_fmac_f32_e32 v188, v143, v47
	v_fmac_f32_e32 v185, v128, v48
	v_fmac_f32_e32 v189, v128, v80
	v_fma_f32 v185, -v144, v80, v185
	v_fmac_f32_e32 v189, v144, v48
	v_fmac_f32_e32 v186, v129, v49
	v_fmac_f32_e32 v190, v129, v81
	v_fma_f32 v186, -v145, v81, v186
	v_fmac_f32_e32 v190, v145, v49
	v_fmac_f32_e32 v183, v130, v50
	v_fmac_f32_e32 v187, v130, v82
	v_fma_f32 v183, -v146, v82, v183
	v_fmac_f32_e32 v187, v146, v50
	v_fmac_f32_e32 v184, v131, v51
	v_fmac_f32_e32 v188, v131, v83
	v_fma_f32 v184, -v147, v83, v184
	v_fmac_f32_e32 v188, v147, v51
	v_fmac_f32_e32 v185, v132, v52
	v_fmac_f32_e32 v189, v132, v84
	v_fma_f32 v185, -v148, v84, v185
	v_fmac_f32_e32 v189, v148, v52
	v_fmac_f32_e32 v186, v133, v53
	v_fmac_f32_e32 v190, v133, v85
	v_fma_f32 v186, -v149, v85, v186
	v_fmac_f32_e32 v190, v149, v53
	s_waitcnt vmcnt(3)
	v_mfma_f32_32x32x16_bf16 v[22:37], v[196:199], v[6:9], 0
	v_mfma_f32_32x32x16_bf16 v[54:69], v[196:199], v[14:17], 0
	v_mfma_f32_32x32x16_bf16 v[38:53], v[196:199], v[10:13], 0
	v_mfma_f32_32x32x16_bf16 v[70:85], v[196:199], v[18:21], 0
	s_add_u32 s42, s32, 0xa0000
	s_addc_u32 s43, s33, 0
	global_load_dwordx4 v[196:199], v210, s[42:43]
	v_add_f32_e32 v219, v175, v176
	v_add_f32_e32 v220, v177, v178
	v_add_f32_e32 v211, v219, v220
	v_add_f32_e32 v219, v179, v180
	v_add_f32_e32 v220, v181, v182
	v_add_f32_e32 v212, v219, v220
	v_add_f32_e32 v219, v183, v184
	v_add_f32_e32 v220, v185, v186
	v_add_f32_e32 v213, v219, v220
	v_add_f32_e32 v219, v187, v188
	v_add_f32_e32 v220, v189, v190
	v_add_f32_e32 v214, v219, v220
	ds_bpermute_b32 v215, v208, v211
	ds_bpermute_b32 v216, v208, v212
	ds_bpermute_b32 v217, v208, v213
	ds_bpermute_b32 v218, v208, v214
	v_mul_f32_e32 v175, v86, v22
	v_mul_f32_e32 v179, v86, v54
	v_fma_f32 v175, -v102, v54, v175
	v_fmac_f32_e32 v179, v102, v22
	v_mul_f32_e32 v176, v87, v23
	v_mul_f32_e32 v180, v87, v55
	v_fma_f32 v176, -v103, v55, v176
	v_fmac_f32_e32 v180, v103, v23
	v_mul_f32_e32 v177, v88, v24
	v_mul_f32_e32 v181, v88, v56
	v_fma_f32 v177, -v104, v56, v177
	v_fmac_f32_e32 v181, v104, v24
	v_mul_f32_e32 v178, v89, v25
	v_mul_f32_e32 v182, v89, v57
	v_fma_f32 v178, -v105, v57, v178
	v_fmac_f32_e32 v182, v105, v25
	v_fmac_f32_e32 v175, v90, v26
	v_fmac_f32_e32 v179, v90, v58
	v_fma_f32 v175, -v106, v58, v175
	v_fmac_f32_e32 v179, v106, v26
	v_fmac_f32_e32 v176, v91, v27
	v_fmac_f32_e32 v180, v91, v59
	v_fma_f32 v176, -v107, v59, v176
	v_fmac_f32_e32 v180, v107, v27
	v_fmac_f32_e32 v177, v92, v28
	v_fmac_f32_e32 v181, v92, v60
	v_fma_f32 v177, -v108, v60, v177
	v_fmac_f32_e32 v181, v108, v28
	v_fmac_f32_e32 v178, v93, v29
	v_fmac_f32_e32 v182, v93, v61
	v_fma_f32 v178, -v109, v61, v178
	v_fmac_f32_e32 v182, v109, v29
	v_fmac_f32_e32 v175, v94, v30
	v_fmac_f32_e32 v179, v94, v62
	v_fma_f32 v175, -v110, v62, v175
	v_fmac_f32_e32 v179, v110, v30
	v_fmac_f32_e32 v176, v95, v31
	v_fmac_f32_e32 v180, v95, v63
	v_fma_f32 v176, -v111, v63, v176
	v_fmac_f32_e32 v180, v111, v31
	v_fmac_f32_e32 v177, v96, v32
	v_fmac_f32_e32 v181, v96, v64
	v_fma_f32 v177, -v112, v64, v177
	v_fmac_f32_e32 v181, v112, v32
	v_fmac_f32_e32 v178, v97, v33
	v_fmac_f32_e32 v182, v97, v65
	v_fma_f32 v178, -v113, v65, v178
	v_fmac_f32_e32 v182, v113, v33
	v_fmac_f32_e32 v175, v98, v34
	v_fmac_f32_e32 v179, v98, v66
	v_fma_f32 v175, -v114, v66, v175
	v_fmac_f32_e32 v179, v114, v34
	v_fmac_f32_e32 v176, v99, v35
	v_fmac_f32_e32 v180, v99, v67
	v_fma_f32 v176, -v115, v67, v176
	v_fmac_f32_e32 v180, v115, v35
	v_fmac_f32_e32 v177, v100, v36
	v_fmac_f32_e32 v181, v100, v68
	v_fma_f32 v177, -v116, v68, v177
	v_fmac_f32_e32 v181, v116, v36
	v_fmac_f32_e32 v178, v101, v37
	v_fmac_f32_e32 v182, v101, v69
	v_fma_f32 v178, -v117, v69, v178
	v_fmac_f32_e32 v182, v117, v37
	s_waitcnt lgkmcnt(0)
	v_add_f32_e32 v211, v211, v215
	v_add_f32_e32 v212, v212, v216
	v_add_f32_e32 v213, v213, v217
	v_add_f32_e32 v214, v214, v218
	v_fma_f32 v219, -v168, v172, v211
	v_fma_f32 v220, v168, v171, v212
	v_fma_f32 v171, v167, v171, v219
	v_fma_f32 v172, v167, v172, v220
	v_fma_f32 v219, -v170, v174, v213
	v_fma_f32 v220, v170, v173, v214
	v_fma_f32 v173, v169, v173, v219
	v_fma_f32 v174, v169, v174, v220
	v_mul_f32_e32 v183, v118, v38
	v_mul_f32_e32 v187, v118, v70
	v_fma_f32 v183, -v134, v70, v183
	v_fmac_f32_e32 v187, v134, v38
	v_mul_f32_e32 v184, v119, v39
	v_mul_f32_e32 v188, v119, v71
	v_fma_f32 v184, -v135, v71, v184
	v_fmac_f32_e32 v188, v135, v39
	v_mul_f32_e32 v185, v120, v40
	v_mul_f32_e32 v189, v120, v72
	v_fma_f32 v185, -v136, v72, v185
	v_fmac_f32_e32 v189, v136, v40
	v_mul_f32_e32 v186, v121, v41
	v_mul_f32_e32 v190, v121, v73
	v_fma_f32 v186, -v137, v73, v186
	v_fmac_f32_e32 v190, v137, v41
	v_fmac_f32_e32 v183, v122, v42
	v_fmac_f32_e32 v187, v122, v74
	v_fma_f32 v183, -v138, v74, v183
	v_fmac_f32_e32 v187, v138, v42
	v_fmac_f32_e32 v184, v123, v43
	v_fmac_f32_e32 v188, v123, v75
	v_fma_f32 v184, -v139, v75, v184
	v_fmac_f32_e32 v188, v139, v43
	v_fmac_f32_e32 v185, v124, v44
	v_fmac_f32_e32 v189, v124, v76
	v_fma_f32 v185, -v140, v76, v185
	v_fmac_f32_e32 v189, v140, v44
	v_fmac_f32_e32 v186, v125, v45
	v_fmac_f32_e32 v190, v125, v77
	v_fma_f32 v186, -v141, v77, v186
	v_fmac_f32_e32 v190, v141, v45
	v_fmac_f32_e32 v183, v126, v46
	v_fmac_f32_e32 v187, v126, v78
	v_fma_f32 v183, -v142, v78, v183
	v_fmac_f32_e32 v187, v142, v46
	v_fmac_f32_e32 v184, v127, v47
	v_fmac_f32_e32 v188, v127, v79
	v_fma_f32 v184, -v143, v79, v184
	v_fmac_f32_e32 v188, v143, v47
	v_fmac_f32_e32 v185, v128, v48
	v_fmac_f32_e32 v189, v128, v80
	v_fma_f32 v185, -v144, v80, v185
	v_fmac_f32_e32 v189, v144, v48
	v_fmac_f32_e32 v186, v129, v49
	v_fmac_f32_e32 v190, v129, v81
	v_fma_f32 v186, -v145, v81, v186
	v_fmac_f32_e32 v190, v145, v49
	v_fmac_f32_e32 v183, v130, v50
	v_fmac_f32_e32 v187, v130, v82
	v_fma_f32 v183, -v146, v82, v183
	v_fmac_f32_e32 v187, v146, v50
	v_fmac_f32_e32 v184, v131, v51
	v_fmac_f32_e32 v188, v131, v83
	v_fma_f32 v184, -v147, v83, v184
	v_fmac_f32_e32 v188, v147, v51
	v_fmac_f32_e32 v185, v132, v52
	v_fmac_f32_e32 v189, v132, v84
	v_fma_f32 v185, -v148, v84, v185
	v_fmac_f32_e32 v189, v148, v52
	v_fmac_f32_e32 v186, v133, v53
	v_fmac_f32_e32 v190, v133, v85
	v_fma_f32 v186, -v149, v85, v186
	v_fmac_f32_e32 v190, v149, v53
	s_waitcnt vmcnt(3)
	v_mfma_f32_32x32x16_bf16 v[22:37], v[200:203], v[6:9], 0
	v_mfma_f32_32x32x16_bf16 v[54:69], v[200:203], v[14:17], 0
	v_mfma_f32_32x32x16_bf16 v[38:53], v[200:203], v[10:13], 0
	v_mfma_f32_32x32x16_bf16 v[70:85], v[200:203], v[18:21], 0
	s_add_u32 s42, s32, 0xc0000
	s_addc_u32 s43, s33, 0
	global_load_dwordx4 v[200:203], v210, s[42:43]
	v_add_f32_e32 v219, v175, v176
	v_add_f32_e32 v220, v177, v178
	v_add_f32_e32 v211, v219, v220
	v_add_f32_e32 v219, v179, v180
	v_add_f32_e32 v220, v181, v182
	v_add_f32_e32 v212, v219, v220
	v_add_f32_e32 v219, v183, v184
	v_add_f32_e32 v220, v185, v186
	v_add_f32_e32 v213, v219, v220
	v_add_f32_e32 v219, v187, v188
	v_add_f32_e32 v220, v189, v190
	v_add_f32_e32 v214, v219, v220
	ds_bpermute_b32 v215, v208, v211
	ds_bpermute_b32 v216, v208, v212
	ds_bpermute_b32 v217, v208, v213
	ds_bpermute_b32 v218, v208, v214
	v_mul_f32_e32 v175, v86, v22
	v_mul_f32_e32 v179, v86, v54
	v_fma_f32 v175, -v102, v54, v175
	v_fmac_f32_e32 v179, v102, v22
	v_mul_f32_e32 v176, v87, v23
	v_mul_f32_e32 v180, v87, v55
	v_fma_f32 v176, -v103, v55, v176
	v_fmac_f32_e32 v180, v103, v23
	v_mul_f32_e32 v177, v88, v24
	v_mul_f32_e32 v181, v88, v56
	v_fma_f32 v177, -v104, v56, v177
	v_fmac_f32_e32 v181, v104, v24
	v_mul_f32_e32 v178, v89, v25
	v_mul_f32_e32 v182, v89, v57
	v_fma_f32 v178, -v105, v57, v178
	v_fmac_f32_e32 v182, v105, v25
	v_fmac_f32_e32 v175, v90, v26
	v_fmac_f32_e32 v179, v90, v58
	v_fma_f32 v175, -v106, v58, v175
	v_fmac_f32_e32 v179, v106, v26
	v_fmac_f32_e32 v176, v91, v27
	v_fmac_f32_e32 v180, v91, v59
	v_fma_f32 v176, -v107, v59, v176
	v_fmac_f32_e32 v180, v107, v27
	v_fmac_f32_e32 v177, v92, v28
	v_fmac_f32_e32 v181, v92, v60
	v_fma_f32 v177, -v108, v60, v177
	v_fmac_f32_e32 v181, v108, v28
	v_fmac_f32_e32 v178, v93, v29
	v_fmac_f32_e32 v182, v93, v61
	v_fma_f32 v178, -v109, v61, v178
	v_fmac_f32_e32 v182, v109, v29
	v_fmac_f32_e32 v175, v94, v30
	v_fmac_f32_e32 v179, v94, v62
	v_fma_f32 v175, -v110, v62, v175
	v_fmac_f32_e32 v179, v110, v30
	v_fmac_f32_e32 v176, v95, v31
	v_fmac_f32_e32 v180, v95, v63
	v_fma_f32 v176, -v111, v63, v176
	v_fmac_f32_e32 v180, v111, v31
	v_fmac_f32_e32 v177, v96, v32
	v_fmac_f32_e32 v181, v96, v64
	v_fma_f32 v177, -v112, v64, v177
	v_fmac_f32_e32 v181, v112, v32
	v_fmac_f32_e32 v178, v97, v33
	v_fmac_f32_e32 v182, v97, v65
	v_fma_f32 v178, -v113, v65, v178
	v_fmac_f32_e32 v182, v113, v33
	v_fmac_f32_e32 v175, v98, v34
	v_fmac_f32_e32 v179, v98, v66
	v_fma_f32 v175, -v114, v66, v175
	v_fmac_f32_e32 v179, v114, v34
	v_fmac_f32_e32 v176, v99, v35
	v_fmac_f32_e32 v180, v99, v67
	v_fma_f32 v176, -v115, v67, v176
	v_fmac_f32_e32 v180, v115, v35
	v_fmac_f32_e32 v177, v100, v36
	v_fmac_f32_e32 v181, v100, v68
	v_fma_f32 v177, -v116, v68, v177
	v_fmac_f32_e32 v181, v116, v36
	v_fmac_f32_e32 v178, v101, v37
	v_fmac_f32_e32 v182, v101, v69
	v_fma_f32 v178, -v117, v69, v178
	v_fmac_f32_e32 v182, v117, v37
	s_waitcnt lgkmcnt(0)
	v_add_f32_e32 v211, v211, v215
	v_add_f32_e32 v212, v212, v216
	v_add_f32_e32 v213, v213, v217
	v_add_f32_e32 v214, v214, v218
	v_fma_f32 v219, -v168, v172, v211
	v_fma_f32 v220, v168, v171, v212
	v_fma_f32 v171, v167, v171, v219
	v_fma_f32 v172, v167, v172, v220
	v_fma_f32 v219, -v170, v174, v213
	v_fma_f32 v220, v170, v173, v214
	v_fma_f32 v173, v169, v173, v219
	v_fma_f32 v174, v169, v174, v220
	v_mul_f32_e32 v183, v118, v38
	v_mul_f32_e32 v187, v118, v70
	v_fma_f32 v183, -v134, v70, v183
	v_fmac_f32_e32 v187, v134, v38
	v_mul_f32_e32 v184, v119, v39
	v_mul_f32_e32 v188, v119, v71
	v_fma_f32 v184, -v135, v71, v184
	v_fmac_f32_e32 v188, v135, v39
	v_mul_f32_e32 v185, v120, v40
	v_mul_f32_e32 v189, v120, v72
	v_fma_f32 v185, -v136, v72, v185
	v_fmac_f32_e32 v189, v136, v40
	v_mul_f32_e32 v186, v121, v41
	v_mul_f32_e32 v190, v121, v73
	v_fma_f32 v186, -v137, v73, v186
	v_fmac_f32_e32 v190, v137, v41
	v_fmac_f32_e32 v183, v122, v42
	v_fmac_f32_e32 v187, v122, v74
	v_fma_f32 v183, -v138, v74, v183
	v_fmac_f32_e32 v187, v138, v42
	v_fmac_f32_e32 v184, v123, v43
	v_fmac_f32_e32 v188, v123, v75
	v_fma_f32 v184, -v139, v75, v184
	v_fmac_f32_e32 v188, v139, v43
	v_fmac_f32_e32 v185, v124, v44
	v_fmac_f32_e32 v189, v124, v76
	v_fma_f32 v185, -v140, v76, v185
	v_fmac_f32_e32 v189, v140, v44
	v_fmac_f32_e32 v186, v125, v45
	v_fmac_f32_e32 v190, v125, v77
	v_fma_f32 v186, -v141, v77, v186
	v_fmac_f32_e32 v190, v141, v45
	v_fmac_f32_e32 v183, v126, v46
	v_fmac_f32_e32 v187, v126, v78
	v_fma_f32 v183, -v142, v78, v183
	v_fmac_f32_e32 v187, v142, v46
	v_fmac_f32_e32 v184, v127, v47
	v_fmac_f32_e32 v188, v127, v79
	v_fma_f32 v184, -v143, v79, v184
	v_fmac_f32_e32 v188, v143, v47
	v_fmac_f32_e32 v185, v128, v48
	v_fmac_f32_e32 v189, v128, v80
	v_fma_f32 v185, -v144, v80, v185
	v_fmac_f32_e32 v189, v144, v48
	v_fmac_f32_e32 v186, v129, v49
	v_fmac_f32_e32 v190, v129, v81
	v_fma_f32 v186, -v145, v81, v186
	v_fmac_f32_e32 v190, v145, v49
	v_fmac_f32_e32 v183, v130, v50
	v_fmac_f32_e32 v187, v130, v82
	v_fma_f32 v183, -v146, v82, v183
	v_fmac_f32_e32 v187, v146, v50
	v_fmac_f32_e32 v184, v131, v51
	v_fmac_f32_e32 v188, v131, v83
	v_fma_f32 v184, -v147, v83, v184
	v_fmac_f32_e32 v188, v147, v51
	v_fmac_f32_e32 v185, v132, v52
	v_fmac_f32_e32 v189, v132, v84
	v_fma_f32 v185, -v148, v84, v185
	v_fmac_f32_e32 v189, v148, v52
	v_fmac_f32_e32 v186, v133, v53
	v_fmac_f32_e32 v190, v133, v85
	v_fma_f32 v186, -v149, v85, v186
	v_fmac_f32_e32 v190, v149, v53
	s_waitcnt vmcnt(3)
	v_mfma_f32_32x32x16_bf16 v[22:37], v[204:207], v[6:9], 0
	v_mfma_f32_32x32x16_bf16 v[54:69], v[204:207], v[14:17], 0
	v_mfma_f32_32x32x16_bf16 v[38:53], v[204:207], v[10:13], 0
	v_mfma_f32_32x32x16_bf16 v[70:85], v[204:207], v[18:21], 0
	s_add_u32 s42, s32, 0xe0000
	s_addc_u32 s43, s33, 0
	global_load_dwordx4 v[204:207], v210, s[42:43]
	v_add_f32_e32 v219, v175, v176
	v_add_f32_e32 v220, v177, v178
	v_add_f32_e32 v211, v219, v220
	v_add_f32_e32 v219, v179, v180
	v_add_f32_e32 v220, v181, v182
	v_add_f32_e32 v212, v219, v220
	v_add_f32_e32 v219, v183, v184
	v_add_f32_e32 v220, v185, v186
	v_add_f32_e32 v213, v219, v220
	v_add_f32_e32 v219, v187, v188
	v_add_f32_e32 v220, v189, v190
	v_add_f32_e32 v214, v219, v220
	ds_bpermute_b32 v215, v208, v211
	ds_bpermute_b32 v216, v208, v212
	ds_bpermute_b32 v217, v208, v213
	ds_bpermute_b32 v218, v208, v214
	v_mul_f32_e32 v175, v86, v22
	v_mul_f32_e32 v179, v86, v54
	v_fma_f32 v175, -v102, v54, v175
	v_fmac_f32_e32 v179, v102, v22
	v_mul_f32_e32 v176, v87, v23
	v_mul_f32_e32 v180, v87, v55
	v_fma_f32 v176, -v103, v55, v176
	v_fmac_f32_e32 v180, v103, v23
	v_mul_f32_e32 v177, v88, v24
	v_mul_f32_e32 v181, v88, v56
	v_fma_f32 v177, -v104, v56, v177
	v_fmac_f32_e32 v181, v104, v24
	v_mul_f32_e32 v178, v89, v25
	v_mul_f32_e32 v182, v89, v57
	v_fma_f32 v178, -v105, v57, v178
	v_fmac_f32_e32 v182, v105, v25
	v_fmac_f32_e32 v175, v90, v26
	v_fmac_f32_e32 v179, v90, v58
	v_fma_f32 v175, -v106, v58, v175
	v_fmac_f32_e32 v179, v106, v26
	v_fmac_f32_e32 v176, v91, v27
	v_fmac_f32_e32 v180, v91, v59
	v_fma_f32 v176, -v107, v59, v176
	v_fmac_f32_e32 v180, v107, v27
	v_fmac_f32_e32 v177, v92, v28
	v_fmac_f32_e32 v181, v92, v60
	v_fma_f32 v177, -v108, v60, v177
	v_fmac_f32_e32 v181, v108, v28
	v_fmac_f32_e32 v178, v93, v29
	v_fmac_f32_e32 v182, v93, v61
	v_fma_f32 v178, -v109, v61, v178
	v_fmac_f32_e32 v182, v109, v29
	v_fmac_f32_e32 v175, v94, v30
	v_fmac_f32_e32 v179, v94, v62
	v_fma_f32 v175, -v110, v62, v175
	v_fmac_f32_e32 v179, v110, v30
	v_fmac_f32_e32 v176, v95, v31
	v_fmac_f32_e32 v180, v95, v63
	v_fma_f32 v176, -v111, v63, v176
	v_fmac_f32_e32 v180, v111, v31
	v_fmac_f32_e32 v177, v96, v32
	v_fmac_f32_e32 v181, v96, v64
	v_fma_f32 v177, -v112, v64, v177
	v_fmac_f32_e32 v181, v112, v32
	v_fmac_f32_e32 v178, v97, v33
	v_fmac_f32_e32 v182, v97, v65
	v_fma_f32 v178, -v113, v65, v178
	v_fmac_f32_e32 v182, v113, v33
	v_fmac_f32_e32 v175, v98, v34
	v_fmac_f32_e32 v179, v98, v66
	v_fma_f32 v175, -v114, v66, v175
	v_fmac_f32_e32 v179, v114, v34
	v_fmac_f32_e32 v176, v99, v35
	v_fmac_f32_e32 v180, v99, v67
	v_fma_f32 v176, -v115, v67, v176
	v_fmac_f32_e32 v180, v115, v35
	v_fmac_f32_e32 v177, v100, v36
	v_fmac_f32_e32 v181, v100, v68
	v_fma_f32 v177, -v116, v68, v177
	v_fmac_f32_e32 v181, v116, v36
	v_fmac_f32_e32 v178, v101, v37
	v_fmac_f32_e32 v182, v101, v69
	v_fma_f32 v178, -v117, v69, v178
	v_fmac_f32_e32 v182, v117, v37
	s_waitcnt lgkmcnt(0)
	v_add_f32_e32 v211, v211, v215
	v_add_f32_e32 v212, v212, v216
	v_add_f32_e32 v213, v213, v217
	v_add_f32_e32 v214, v214, v218
	v_fma_f32 v219, -v168, v172, v211
	v_fma_f32 v220, v168, v171, v212
	v_fma_f32 v171, v167, v171, v219
	v_fma_f32 v172, v167, v172, v220
	v_fma_f32 v219, -v170, v174, v213
	v_fma_f32 v220, v170, v173, v214
	v_fma_f32 v173, v169, v173, v219
	v_fma_f32 v174, v169, v174, v220
	v_mul_f32_e32 v183, v118, v38
	v_mul_f32_e32 v187, v118, v70
	v_fma_f32 v183, -v134, v70, v183
	v_fmac_f32_e32 v187, v134, v38
	v_mul_f32_e32 v184, v119, v39
	v_mul_f32_e32 v188, v119, v71
	v_fma_f32 v184, -v135, v71, v184
	v_fmac_f32_e32 v188, v135, v39
	v_mul_f32_e32 v185, v120, v40
	v_mul_f32_e32 v189, v120, v72
	v_fma_f32 v185, -v136, v72, v185
	v_fmac_f32_e32 v189, v136, v40
	v_mul_f32_e32 v186, v121, v41
	v_mul_f32_e32 v190, v121, v73
	v_fma_f32 v186, -v137, v73, v186
	v_fmac_f32_e32 v190, v137, v41
	v_fmac_f32_e32 v183, v122, v42
	v_fmac_f32_e32 v187, v122, v74
	v_fma_f32 v183, -v138, v74, v183
	v_fmac_f32_e32 v187, v138, v42
	v_fmac_f32_e32 v184, v123, v43
	v_fmac_f32_e32 v188, v123, v75
	v_fma_f32 v184, -v139, v75, v184
	v_fmac_f32_e32 v188, v139, v43
	v_fmac_f32_e32 v185, v124, v44
	v_fmac_f32_e32 v189, v124, v76
	v_fma_f32 v185, -v140, v76, v185
	v_fmac_f32_e32 v189, v140, v44
	v_fmac_f32_e32 v186, v125, v45
	v_fmac_f32_e32 v190, v125, v77
	v_fma_f32 v186, -v141, v77, v186
	v_fmac_f32_e32 v190, v141, v45
	v_fmac_f32_e32 v183, v126, v46
	v_fmac_f32_e32 v187, v126, v78
	v_fma_f32 v183, -v142, v78, v183
	v_fmac_f32_e32 v187, v142, v46
	v_fmac_f32_e32 v184, v127, v47
	v_fmac_f32_e32 v188, v127, v79
	v_fma_f32 v184, -v143, v79, v184
	v_fmac_f32_e32 v188, v143, v47
	v_fmac_f32_e32 v185, v128, v48
	v_fmac_f32_e32 v189, v128, v80
	v_fma_f32 v185, -v144, v80, v185
	v_fmac_f32_e32 v189, v144, v48
	v_fmac_f32_e32 v186, v129, v49
	v_fmac_f32_e32 v190, v129, v81
	v_fma_f32 v186, -v145, v81, v186
	v_fmac_f32_e32 v190, v145, v49
	v_fmac_f32_e32 v183, v130, v50
	v_fmac_f32_e32 v187, v130, v82
	v_fma_f32 v183, -v146, v82, v183
	v_fmac_f32_e32 v187, v146, v50
	v_fmac_f32_e32 v184, v131, v51
	v_fmac_f32_e32 v188, v131, v83
	v_fma_f32 v184, -v147, v83, v184
	v_fmac_f32_e32 v188, v147, v51
	v_fmac_f32_e32 v185, v132, v52
	v_fmac_f32_e32 v189, v132, v84
	v_fma_f32 v185, -v148, v84, v185
	v_fmac_f32_e32 v189, v148, v52
	v_fmac_f32_e32 v186, v133, v53
	v_fmac_f32_e32 v190, v133, v85
	v_fma_f32 v186, -v149, v85, v186
	v_fmac_f32_e32 v190, v149, v53
	s_waitcnt vmcnt(3)
	v_mfma_f32_32x32x16_bf16 v[22:37], v[192:195], v[6:9], 0
	v_mfma_f32_32x32x16_bf16 v[54:69], v[192:195], v[14:17], 0
	v_mfma_f32_32x32x16_bf16 v[38:53], v[192:195], v[10:13], 0
	v_mfma_f32_32x32x16_bf16 v[70:85], v[192:195], v[18:21], 0
	s_add_u32 s42, s32, 0x100000
	s_addc_u32 s43, s33, 0
	global_load_dwordx4 v[192:195], v210, s[42:43]
	v_add_f32_e32 v219, v175, v176
	v_add_f32_e32 v220, v177, v178
	v_add_f32_e32 v211, v219, v220
	v_add_f32_e32 v219, v179, v180
	v_add_f32_e32 v220, v181, v182
	v_add_f32_e32 v212, v219, v220
	v_add_f32_e32 v219, v183, v184
	v_add_f32_e32 v220, v185, v186
	v_add_f32_e32 v213, v219, v220
	v_add_f32_e32 v219, v187, v188
	v_add_f32_e32 v220, v189, v190
	v_add_f32_e32 v214, v219, v220
	ds_bpermute_b32 v215, v208, v211
	ds_bpermute_b32 v216, v208, v212
	ds_bpermute_b32 v217, v208, v213
	ds_bpermute_b32 v218, v208, v214
	v_mul_f32_e32 v175, v86, v22
	v_mul_f32_e32 v179, v86, v54
	v_fma_f32 v175, -v102, v54, v175
	v_fmac_f32_e32 v179, v102, v22
	v_mul_f32_e32 v176, v87, v23
	v_mul_f32_e32 v180, v87, v55
	v_fma_f32 v176, -v103, v55, v176
	v_fmac_f32_e32 v180, v103, v23
	v_mul_f32_e32 v177, v88, v24
	v_mul_f32_e32 v181, v88, v56
	v_fma_f32 v177, -v104, v56, v177
	v_fmac_f32_e32 v181, v104, v24
	v_mul_f32_e32 v178, v89, v25
	v_mul_f32_e32 v182, v89, v57
	v_fma_f32 v178, -v105, v57, v178
	v_fmac_f32_e32 v182, v105, v25
	v_fmac_f32_e32 v175, v90, v26
	v_fmac_f32_e32 v179, v90, v58
	v_fma_f32 v175, -v106, v58, v175
	v_fmac_f32_e32 v179, v106, v26
	v_fmac_f32_e32 v176, v91, v27
	v_fmac_f32_e32 v180, v91, v59
	v_fma_f32 v176, -v107, v59, v176
	v_fmac_f32_e32 v180, v107, v27
	v_fmac_f32_e32 v177, v92, v28
	v_fmac_f32_e32 v181, v92, v60
	v_fma_f32 v177, -v108, v60, v177
	v_fmac_f32_e32 v181, v108, v28
	v_fmac_f32_e32 v178, v93, v29
	v_fmac_f32_e32 v182, v93, v61
	v_fma_f32 v178, -v109, v61, v178
	v_fmac_f32_e32 v182, v109, v29
	v_fmac_f32_e32 v175, v94, v30
	v_fmac_f32_e32 v179, v94, v62
	v_fma_f32 v175, -v110, v62, v175
	v_fmac_f32_e32 v179, v110, v30
	v_fmac_f32_e32 v176, v95, v31
	v_fmac_f32_e32 v180, v95, v63
	v_fma_f32 v176, -v111, v63, v176
	v_fmac_f32_e32 v180, v111, v31
	v_fmac_f32_e32 v177, v96, v32
	v_fmac_f32_e32 v181, v96, v64
	v_fma_f32 v177, -v112, v64, v177
	v_fmac_f32_e32 v181, v112, v32
	v_fmac_f32_e32 v178, v97, v33
	v_fmac_f32_e32 v182, v97, v65
	v_fma_f32 v178, -v113, v65, v178
	v_fmac_f32_e32 v182, v113, v33
	v_fmac_f32_e32 v175, v98, v34
	v_fmac_f32_e32 v179, v98, v66
	v_fma_f32 v175, -v114, v66, v175
	v_fmac_f32_e32 v179, v114, v34
	v_fmac_f32_e32 v176, v99, v35
	v_fmac_f32_e32 v180, v99, v67
	v_fma_f32 v176, -v115, v67, v176
	v_fmac_f32_e32 v180, v115, v35
	v_fmac_f32_e32 v177, v100, v36
	v_fmac_f32_e32 v181, v100, v68
	v_fma_f32 v177, -v116, v68, v177
	v_fmac_f32_e32 v181, v116, v36
	v_fmac_f32_e32 v178, v101, v37
	v_fmac_f32_e32 v182, v101, v69
	v_fma_f32 v178, -v117, v69, v178
	v_fmac_f32_e32 v182, v117, v37
	s_waitcnt lgkmcnt(0)
	v_add_f32_e32 v211, v211, v215
	v_add_f32_e32 v212, v212, v216
	v_add_f32_e32 v213, v213, v217
	v_add_f32_e32 v214, v214, v218
	v_fma_f32 v219, -v168, v172, v211
	v_fma_f32 v220, v168, v171, v212
	v_fma_f32 v171, v167, v171, v219
	v_fma_f32 v172, v167, v172, v220
	v_fma_f32 v219, -v170, v174, v213
	v_fma_f32 v220, v170, v173, v214
	v_fma_f32 v173, v169, v173, v219
	v_fma_f32 v174, v169, v174, v220
	s_add_u32 s42, s38, 0x0
	s_addc_u32 s43, s39, 0
	s_mov_b64 exec, s[12:13]
	global_store_dword v209, v171, s[42:43]
	global_store_dword v209, v172, s[42:43] offset:256
	global_store_dword v209, v173, s[42:43] offset:128
	global_store_dword v209, v174, s[42:43] offset:384
	s_mov_b64 exec, -1
	v_mul_f32_e32 v183, v118, v38
	v_mul_f32_e32 v187, v118, v70
	v_fma_f32 v183, -v134, v70, v183
	v_fmac_f32_e32 v187, v134, v38
	v_mul_f32_e32 v184, v119, v39
	v_mul_f32_e32 v188, v119, v71
	v_fma_f32 v184, -v135, v71, v184
	v_fmac_f32_e32 v188, v135, v39
	v_mul_f32_e32 v185, v120, v40
	v_mul_f32_e32 v189, v120, v72
	v_fma_f32 v185, -v136, v72, v185
	v_fmac_f32_e32 v189, v136, v40
	v_mul_f32_e32 v186, v121, v41
	v_mul_f32_e32 v190, v121, v73
	v_fma_f32 v186, -v137, v73, v186
	v_fmac_f32_e32 v190, v137, v41
	v_fmac_f32_e32 v183, v122, v42
	v_fmac_f32_e32 v187, v122, v74
	v_fma_f32 v183, -v138, v74, v183
	v_fmac_f32_e32 v187, v138, v42
	v_fmac_f32_e32 v184, v123, v43
	v_fmac_f32_e32 v188, v123, v75
	v_fma_f32 v184, -v139, v75, v184
	v_fmac_f32_e32 v188, v139, v43
	v_fmac_f32_e32 v185, v124, v44
	v_fmac_f32_e32 v189, v124, v76
	v_fma_f32 v185, -v140, v76, v185
	v_fmac_f32_e32 v189, v140, v44
	v_fmac_f32_e32 v186, v125, v45
	v_fmac_f32_e32 v190, v125, v77
	v_fma_f32 v186, -v141, v77, v186
	v_fmac_f32_e32 v190, v141, v45
	v_fmac_f32_e32 v183, v126, v46
	v_fmac_f32_e32 v187, v126, v78
	v_fma_f32 v183, -v142, v78, v183
	v_fmac_f32_e32 v187, v142, v46
	v_fmac_f32_e32 v184, v127, v47
	v_fmac_f32_e32 v188, v127, v79
	v_fma_f32 v184, -v143, v79, v184
	v_fmac_f32_e32 v188, v143, v47
	v_fmac_f32_e32 v185, v128, v48
	v_fmac_f32_e32 v189, v128, v80
	v_fma_f32 v185, -v144, v80, v185
	v_fmac_f32_e32 v189, v144, v48
	v_fmac_f32_e32 v186, v129, v49
	v_fmac_f32_e32 v190, v129, v81
	v_fma_f32 v186, -v145, v81, v186
	v_fmac_f32_e32 v190, v145, v49
	v_fmac_f32_e32 v183, v130, v50
	v_fmac_f32_e32 v187, v130, v82
	v_fma_f32 v183, -v146, v82, v183
	v_fmac_f32_e32 v187, v146, v50
	v_fmac_f32_e32 v184, v131, v51
	v_fmac_f32_e32 v188, v131, v83
	v_fma_f32 v184, -v147, v83, v184
	v_fmac_f32_e32 v188, v147, v51
	v_fmac_f32_e32 v185, v132, v52
	v_fmac_f32_e32 v189, v132, v84
	v_fma_f32 v185, -v148, v84, v185
	v_fmac_f32_e32 v189, v148, v52
	v_fmac_f32_e32 v186, v133, v53
	v_fmac_f32_e32 v190, v133, v85
	v_fma_f32 v186, -v149, v85, v186
	v_fmac_f32_e32 v190, v149, v53
	s_waitcnt vmcnt(7)
	v_mfma_f32_32x32x16_bf16 v[22:37], v[196:199], v[6:9], 0
	v_mfma_f32_32x32x16_bf16 v[54:69], v[196:199], v[14:17], 0
	v_mfma_f32_32x32x16_bf16 v[38:53], v[196:199], v[10:13], 0
	v_mfma_f32_32x32x16_bf16 v[70:85], v[196:199], v[18:21], 0
	s_add_u32 s42, s32, 0x120000
	s_addc_u32 s43, s33, 0
	global_load_dwordx4 v[196:199], v210, s[42:43]
	v_add_f32_e32 v219, v175, v176
	v_add_f32_e32 v220, v177, v178
	v_add_f32_e32 v211, v219, v220
	v_add_f32_e32 v219, v179, v180
	v_add_f32_e32 v220, v181, v182
	v_add_f32_e32 v212, v219, v220
	v_add_f32_e32 v219, v183, v184
	v_add_f32_e32 v220, v185, v186
	v_add_f32_e32 v213, v219, v220
	v_add_f32_e32 v219, v187, v188
	v_add_f32_e32 v220, v189, v190
	v_add_f32_e32 v214, v219, v220
	ds_bpermute_b32 v215, v208, v211
	ds_bpermute_b32 v216, v208, v212
	ds_bpermute_b32 v217, v208, v213
	ds_bpermute_b32 v218, v208, v214
	v_mul_f32_e32 v175, v86, v22
	v_mul_f32_e32 v179, v86, v54
	v_fma_f32 v175, -v102, v54, v175
	v_fmac_f32_e32 v179, v102, v22
	v_mul_f32_e32 v176, v87, v23
	v_mul_f32_e32 v180, v87, v55
	v_fma_f32 v176, -v103, v55, v176
	v_fmac_f32_e32 v180, v103, v23
	v_mul_f32_e32 v177, v88, v24
	v_mul_f32_e32 v181, v88, v56
	v_fma_f32 v177, -v104, v56, v177
	v_fmac_f32_e32 v181, v104, v24
	v_mul_f32_e32 v178, v89, v25
	v_mul_f32_e32 v182, v89, v57
	v_fma_f32 v178, -v105, v57, v178
	v_fmac_f32_e32 v182, v105, v25
	v_fmac_f32_e32 v175, v90, v26
	v_fmac_f32_e32 v179, v90, v58
	v_fma_f32 v175, -v106, v58, v175
	v_fmac_f32_e32 v179, v106, v26
	v_fmac_f32_e32 v176, v91, v27
	v_fmac_f32_e32 v180, v91, v59
	v_fma_f32 v176, -v107, v59, v176
	v_fmac_f32_e32 v180, v107, v27
	v_fmac_f32_e32 v177, v92, v28
	v_fmac_f32_e32 v181, v92, v60
	v_fma_f32 v177, -v108, v60, v177
	v_fmac_f32_e32 v181, v108, v28
	v_fmac_f32_e32 v178, v93, v29
	v_fmac_f32_e32 v182, v93, v61
	v_fma_f32 v178, -v109, v61, v178
	v_fmac_f32_e32 v182, v109, v29
	v_fmac_f32_e32 v175, v94, v30
	v_fmac_f32_e32 v179, v94, v62
	v_fma_f32 v175, -v110, v62, v175
	v_fmac_f32_e32 v179, v110, v30
	v_fmac_f32_e32 v176, v95, v31
	v_fmac_f32_e32 v180, v95, v63
	v_fma_f32 v176, -v111, v63, v176
	v_fmac_f32_e32 v180, v111, v31
	v_fmac_f32_e32 v177, v96, v32
	v_fmac_f32_e32 v181, v96, v64
	v_fma_f32 v177, -v112, v64, v177
	v_fmac_f32_e32 v181, v112, v32
	v_fmac_f32_e32 v178, v97, v33
	v_fmac_f32_e32 v182, v97, v65
	v_fma_f32 v178, -v113, v65, v178
	v_fmac_f32_e32 v182, v113, v33
	v_fmac_f32_e32 v175, v98, v34
	v_fmac_f32_e32 v179, v98, v66
	v_fma_f32 v175, -v114, v66, v175
	v_fmac_f32_e32 v179, v114, v34
	v_fmac_f32_e32 v176, v99, v35
	v_fmac_f32_e32 v180, v99, v67
	v_fma_f32 v176, -v115, v67, v176
	v_fmac_f32_e32 v180, v115, v35
	v_fmac_f32_e32 v177, v100, v36
	v_fmac_f32_e32 v181, v100, v68
	v_fma_f32 v177, -v116, v68, v177
	v_fmac_f32_e32 v181, v116, v36
	v_fmac_f32_e32 v178, v101, v37
	v_fmac_f32_e32 v182, v101, v69
	v_fma_f32 v178, -v117, v69, v178
	v_fmac_f32_e32 v182, v117, v37
	s_waitcnt lgkmcnt(0)
	v_add_f32_e32 v211, v211, v215
	v_add_f32_e32 v212, v212, v216
	v_add_f32_e32 v213, v213, v217
	v_add_f32_e32 v214, v214, v218
	v_fma_f32 v219, -v168, v172, v211
	v_fma_f32 v220, v168, v171, v212
	v_fma_f32 v171, v167, v171, v219
	v_fma_f32 v172, v167, v172, v220
	v_fma_f32 v219, -v170, v174, v213
	v_fma_f32 v220, v170, v173, v214
	v_fma_f32 v173, v169, v173, v219
	v_fma_f32 v174, v169, v174, v220
	v_mul_f32_e32 v183, v118, v38
	v_mul_f32_e32 v187, v118, v70
	v_fma_f32 v183, -v134, v70, v183
	v_fmac_f32_e32 v187, v134, v38
	v_mul_f32_e32 v184, v119, v39
	v_mul_f32_e32 v188, v119, v71
	v_fma_f32 v184, -v135, v71, v184
	v_fmac_f32_e32 v188, v135, v39
	v_mul_f32_e32 v185, v120, v40
	v_mul_f32_e32 v189, v120, v72
	v_fma_f32 v185, -v136, v72, v185
	v_fmac_f32_e32 v189, v136, v40
	v_mul_f32_e32 v186, v121, v41
	v_mul_f32_e32 v190, v121, v73
	v_fma_f32 v186, -v137, v73, v186
	v_fmac_f32_e32 v190, v137, v41
	v_fmac_f32_e32 v183, v122, v42
	v_fmac_f32_e32 v187, v122, v74
	v_fma_f32 v183, -v138, v74, v183
	v_fmac_f32_e32 v187, v138, v42
	v_fmac_f32_e32 v184, v123, v43
	v_fmac_f32_e32 v188, v123, v75
	v_fma_f32 v184, -v139, v75, v184
	v_fmac_f32_e32 v188, v139, v43
	v_fmac_f32_e32 v185, v124, v44
	v_fmac_f32_e32 v189, v124, v76
	v_fma_f32 v185, -v140, v76, v185
	v_fmac_f32_e32 v189, v140, v44
	v_fmac_f32_e32 v186, v125, v45
	v_fmac_f32_e32 v190, v125, v77
	v_fma_f32 v186, -v141, v77, v186
	v_fmac_f32_e32 v190, v141, v45
	v_fmac_f32_e32 v183, v126, v46
	v_fmac_f32_e32 v187, v126, v78
	v_fma_f32 v183, -v142, v78, v183
	v_fmac_f32_e32 v187, v142, v46
	v_fmac_f32_e32 v184, v127, v47
	v_fmac_f32_e32 v188, v127, v79
	v_fma_f32 v184, -v143, v79, v184
	v_fmac_f32_e32 v188, v143, v47
	v_fmac_f32_e32 v185, v128, v48
	v_fmac_f32_e32 v189, v128, v80
	v_fma_f32 v185, -v144, v80, v185
	v_fmac_f32_e32 v189, v144, v48
	v_fmac_f32_e32 v186, v129, v49
	v_fmac_f32_e32 v190, v129, v81
	v_fma_f32 v186, -v145, v81, v186
	v_fmac_f32_e32 v190, v145, v49
	v_fmac_f32_e32 v183, v130, v50
	v_fmac_f32_e32 v187, v130, v82
	v_fma_f32 v183, -v146, v82, v183
	v_fmac_f32_e32 v187, v146, v50
	v_fmac_f32_e32 v184, v131, v51
	v_fmac_f32_e32 v188, v131, v83
	v_fma_f32 v184, -v147, v83, v184
	v_fmac_f32_e32 v188, v147, v51
	v_fmac_f32_e32 v185, v132, v52
	v_fmac_f32_e32 v189, v132, v84
	v_fma_f32 v185, -v148, v84, v185
	v_fmac_f32_e32 v189, v148, v52
	v_fmac_f32_e32 v186, v133, v53
	v_fmac_f32_e32 v190, v133, v85
	v_fma_f32 v186, -v149, v85, v186
	v_fmac_f32_e32 v190, v149, v53
	s_waitcnt vmcnt(7)
	v_mfma_f32_32x32x16_bf16 v[22:37], v[200:203], v[6:9], 0
	v_mfma_f32_32x32x16_bf16 v[54:69], v[200:203], v[14:17], 0
	v_mfma_f32_32x32x16_bf16 v[38:53], v[200:203], v[10:13], 0
	v_mfma_f32_32x32x16_bf16 v[70:85], v[200:203], v[18:21], 0
	s_add_u32 s42, s32, 0x140000
	s_addc_u32 s43, s33, 0
	global_load_dwordx4 v[200:203], v210, s[42:43]
	v_add_f32_e32 v219, v175, v176
	v_add_f32_e32 v220, v177, v178
	v_add_f32_e32 v211, v219, v220
	v_add_f32_e32 v219, v179, v180
	v_add_f32_e32 v220, v181, v182
	v_add_f32_e32 v212, v219, v220
	v_add_f32_e32 v219, v183, v184
	v_add_f32_e32 v220, v185, v186
	v_add_f32_e32 v213, v219, v220
	v_add_f32_e32 v219, v187, v188
	v_add_f32_e32 v220, v189, v190
	v_add_f32_e32 v214, v219, v220
	ds_bpermute_b32 v215, v208, v211
	ds_bpermute_b32 v216, v208, v212
	ds_bpermute_b32 v217, v208, v213
	ds_bpermute_b32 v218, v208, v214
	v_mul_f32_e32 v175, v86, v22
	v_mul_f32_e32 v179, v86, v54
	v_fma_f32 v175, -v102, v54, v175
	v_fmac_f32_e32 v179, v102, v22
	v_mul_f32_e32 v176, v87, v23
	v_mul_f32_e32 v180, v87, v55
	v_fma_f32 v176, -v103, v55, v176
	v_fmac_f32_e32 v180, v103, v23
	v_mul_f32_e32 v177, v88, v24
	v_mul_f32_e32 v181, v88, v56
	v_fma_f32 v177, -v104, v56, v177
	v_fmac_f32_e32 v181, v104, v24
	v_mul_f32_e32 v178, v89, v25
	v_mul_f32_e32 v182, v89, v57
	v_fma_f32 v178, -v105, v57, v178
	v_fmac_f32_e32 v182, v105, v25
	v_fmac_f32_e32 v175, v90, v26
	v_fmac_f32_e32 v179, v90, v58
	v_fma_f32 v175, -v106, v58, v175
	v_fmac_f32_e32 v179, v106, v26
	v_fmac_f32_e32 v176, v91, v27
	v_fmac_f32_e32 v180, v91, v59
	v_fma_f32 v176, -v107, v59, v176
	v_fmac_f32_e32 v180, v107, v27
	v_fmac_f32_e32 v177, v92, v28
	v_fmac_f32_e32 v181, v92, v60
	v_fma_f32 v177, -v108, v60, v177
	v_fmac_f32_e32 v181, v108, v28
	v_fmac_f32_e32 v178, v93, v29
	v_fmac_f32_e32 v182, v93, v61
	v_fma_f32 v178, -v109, v61, v178
	v_fmac_f32_e32 v182, v109, v29
	v_fmac_f32_e32 v175, v94, v30
	v_fmac_f32_e32 v179, v94, v62
	v_fma_f32 v175, -v110, v62, v175
	v_fmac_f32_e32 v179, v110, v30
	v_fmac_f32_e32 v176, v95, v31
	v_fmac_f32_e32 v180, v95, v63
	v_fma_f32 v176, -v111, v63, v176
	v_fmac_f32_e32 v180, v111, v31
	v_fmac_f32_e32 v177, v96, v32
	v_fmac_f32_e32 v181, v96, v64
	v_fma_f32 v177, -v112, v64, v177
	v_fmac_f32_e32 v181, v112, v32
	v_fmac_f32_e32 v178, v97, v33
	v_fmac_f32_e32 v182, v97, v65
	v_fma_f32 v178, -v113, v65, v178
	v_fmac_f32_e32 v182, v113, v33
	v_fmac_f32_e32 v175, v98, v34
	v_fmac_f32_e32 v179, v98, v66
	v_fma_f32 v175, -v114, v66, v175
	v_fmac_f32_e32 v179, v114, v34
	v_fmac_f32_e32 v176, v99, v35
	v_fmac_f32_e32 v180, v99, v67
	v_fma_f32 v176, -v115, v67, v176
	v_fmac_f32_e32 v180, v115, v35
	v_fmac_f32_e32 v177, v100, v36
	v_fmac_f32_e32 v181, v100, v68
	v_fma_f32 v177, -v116, v68, v177
	v_fmac_f32_e32 v181, v116, v36
	v_fmac_f32_e32 v178, v101, v37
	v_fmac_f32_e32 v182, v101, v69
	v_fma_f32 v178, -v117, v69, v178
	v_fmac_f32_e32 v182, v117, v37
	s_waitcnt lgkmcnt(0)
	v_add_f32_e32 v211, v211, v215
	v_add_f32_e32 v212, v212, v216
	v_add_f32_e32 v213, v213, v217
	v_add_f32_e32 v214, v214, v218
	v_fma_f32 v219, -v168, v172, v211
	v_fma_f32 v220, v168, v171, v212
	v_fma_f32 v171, v167, v171, v219
	v_fma_f32 v172, v167, v172, v220
	v_fma_f32 v219, -v170, v174, v213
	v_fma_f32 v220, v170, v173, v214
	v_fma_f32 v173, v169, v173, v219
	v_fma_f32 v174, v169, v174, v220
	v_mul_f32_e32 v183, v118, v38
	v_mul_f32_e32 v187, v118, v70
	v_fma_f32 v183, -v134, v70, v183
	v_fmac_f32_e32 v187, v134, v38
	v_mul_f32_e32 v184, v119, v39
	v_mul_f32_e32 v188, v119, v71
	v_fma_f32 v184, -v135, v71, v184
	v_fmac_f32_e32 v188, v135, v39
	v_mul_f32_e32 v185, v120, v40
	v_mul_f32_e32 v189, v120, v72
	v_fma_f32 v185, -v136, v72, v185
	v_fmac_f32_e32 v189, v136, v40
	v_mul_f32_e32 v186, v121, v41
	v_mul_f32_e32 v190, v121, v73
	v_fma_f32 v186, -v137, v73, v186
	v_fmac_f32_e32 v190, v137, v41
	v_fmac_f32_e32 v183, v122, v42
	v_fmac_f32_e32 v187, v122, v74
	v_fma_f32 v183, -v138, v74, v183
	v_fmac_f32_e32 v187, v138, v42
	v_fmac_f32_e32 v184, v123, v43
	v_fmac_f32_e32 v188, v123, v75
	v_fma_f32 v184, -v139, v75, v184
	v_fmac_f32_e32 v188, v139, v43
	v_fmac_f32_e32 v185, v124, v44
	v_fmac_f32_e32 v189, v124, v76
	v_fma_f32 v185, -v140, v76, v185
	v_fmac_f32_e32 v189, v140, v44
	v_fmac_f32_e32 v186, v125, v45
	v_fmac_f32_e32 v190, v125, v77
	v_fma_f32 v186, -v141, v77, v186
	v_fmac_f32_e32 v190, v141, v45
	v_fmac_f32_e32 v183, v126, v46
	v_fmac_f32_e32 v187, v126, v78
	v_fma_f32 v183, -v142, v78, v183
	v_fmac_f32_e32 v187, v142, v46
	v_fmac_f32_e32 v184, v127, v47
	v_fmac_f32_e32 v188, v127, v79
	v_fma_f32 v184, -v143, v79, v184
	v_fmac_f32_e32 v188, v143, v47
	v_fmac_f32_e32 v185, v128, v48
	v_fmac_f32_e32 v189, v128, v80
	v_fma_f32 v185, -v144, v80, v185
	v_fmac_f32_e32 v189, v144, v48
	v_fmac_f32_e32 v186, v129, v49
	v_fmac_f32_e32 v190, v129, v81
	v_fma_f32 v186, -v145, v81, v186
	v_fmac_f32_e32 v190, v145, v49
	v_fmac_f32_e32 v183, v130, v50
	v_fmac_f32_e32 v187, v130, v82
	v_fma_f32 v183, -v146, v82, v183
	v_fmac_f32_e32 v187, v146, v50
	v_fmac_f32_e32 v184, v131, v51
	v_fmac_f32_e32 v188, v131, v83
	v_fma_f32 v184, -v147, v83, v184
	v_fmac_f32_e32 v188, v147, v51
	v_fmac_f32_e32 v185, v132, v52
	v_fmac_f32_e32 v189, v132, v84
	v_fma_f32 v185, -v148, v84, v185
	v_fmac_f32_e32 v189, v148, v52
	v_fmac_f32_e32 v186, v133, v53
	v_fmac_f32_e32 v190, v133, v85
	v_fma_f32 v186, -v149, v85, v186
	v_fmac_f32_e32 v190, v149, v53
	s_waitcnt vmcnt(7)
	v_mfma_f32_32x32x16_bf16 v[22:37], v[204:207], v[6:9], 0
	v_mfma_f32_32x32x16_bf16 v[54:69], v[204:207], v[14:17], 0
	v_mfma_f32_32x32x16_bf16 v[38:53], v[204:207], v[10:13], 0
	v_mfma_f32_32x32x16_bf16 v[70:85], v[204:207], v[18:21], 0
	s_add_u32 s42, s32, 0x160000
	s_addc_u32 s43, s33, 0
	global_load_dwordx4 v[204:207], v210, s[42:43]
	v_add_f32_e32 v219, v175, v176
	v_add_f32_e32 v220, v177, v178
	v_add_f32_e32 v211, v219, v220
	v_add_f32_e32 v219, v179, v180
	v_add_f32_e32 v220, v181, v182
	v_add_f32_e32 v212, v219, v220
	v_add_f32_e32 v219, v183, v184
	v_add_f32_e32 v220, v185, v186
	v_add_f32_e32 v213, v219, v220
	v_add_f32_e32 v219, v187, v188
	v_add_f32_e32 v220, v189, v190
	v_add_f32_e32 v214, v219, v220
	ds_bpermute_b32 v215, v208, v211
	ds_bpermute_b32 v216, v208, v212
	ds_bpermute_b32 v217, v208, v213
	ds_bpermute_b32 v218, v208, v214
	v_mul_f32_e32 v175, v86, v22
	v_mul_f32_e32 v179, v86, v54
	v_fma_f32 v175, -v102, v54, v175
	v_fmac_f32_e32 v179, v102, v22
	v_mul_f32_e32 v176, v87, v23
	v_mul_f32_e32 v180, v87, v55
	v_fma_f32 v176, -v103, v55, v176
	v_fmac_f32_e32 v180, v103, v23
	v_mul_f32_e32 v177, v88, v24
	v_mul_f32_e32 v181, v88, v56
	v_fma_f32 v177, -v104, v56, v177
	v_fmac_f32_e32 v181, v104, v24
	v_mul_f32_e32 v178, v89, v25
	v_mul_f32_e32 v182, v89, v57
	v_fma_f32 v178, -v105, v57, v178
	v_fmac_f32_e32 v182, v105, v25
	v_fmac_f32_e32 v175, v90, v26
	v_fmac_f32_e32 v179, v90, v58
	v_fma_f32 v175, -v106, v58, v175
	v_fmac_f32_e32 v179, v106, v26
	v_fmac_f32_e32 v176, v91, v27
	v_fmac_f32_e32 v180, v91, v59
	v_fma_f32 v176, -v107, v59, v176
	v_fmac_f32_e32 v180, v107, v27
	v_fmac_f32_e32 v177, v92, v28
	v_fmac_f32_e32 v181, v92, v60
	v_fma_f32 v177, -v108, v60, v177
	v_fmac_f32_e32 v181, v108, v28
	v_fmac_f32_e32 v178, v93, v29
	v_fmac_f32_e32 v182, v93, v61
	v_fma_f32 v178, -v109, v61, v178
	v_fmac_f32_e32 v182, v109, v29
	v_fmac_f32_e32 v175, v94, v30
	v_fmac_f32_e32 v179, v94, v62
	v_fma_f32 v175, -v110, v62, v175
	v_fmac_f32_e32 v179, v110, v30
	v_fmac_f32_e32 v176, v95, v31
	v_fmac_f32_e32 v180, v95, v63
	v_fma_f32 v176, -v111, v63, v176
	v_fmac_f32_e32 v180, v111, v31
	v_fmac_f32_e32 v177, v96, v32
	v_fmac_f32_e32 v181, v96, v64
	v_fma_f32 v177, -v112, v64, v177
	v_fmac_f32_e32 v181, v112, v32
	v_fmac_f32_e32 v178, v97, v33
	v_fmac_f32_e32 v182, v97, v65
	v_fma_f32 v178, -v113, v65, v178
	v_fmac_f32_e32 v182, v113, v33
	v_fmac_f32_e32 v175, v98, v34
	v_fmac_f32_e32 v179, v98, v66
	v_fma_f32 v175, -v114, v66, v175
	v_fmac_f32_e32 v179, v114, v34
	v_fmac_f32_e32 v176, v99, v35
	v_fmac_f32_e32 v180, v99, v67
	v_fma_f32 v176, -v115, v67, v176
	v_fmac_f32_e32 v180, v115, v35
	v_fmac_f32_e32 v177, v100, v36
	v_fmac_f32_e32 v181, v100, v68
	v_fma_f32 v177, -v116, v68, v177
	v_fmac_f32_e32 v181, v116, v36
	v_fmac_f32_e32 v178, v101, v37
	v_fmac_f32_e32 v182, v101, v69
	v_fma_f32 v178, -v117, v69, v178
	v_fmac_f32_e32 v182, v117, v37
	s_waitcnt lgkmcnt(0)
	v_add_f32_e32 v211, v211, v215
	v_add_f32_e32 v212, v212, v216
	v_add_f32_e32 v213, v213, v217
	v_add_f32_e32 v214, v214, v218
	v_fma_f32 v219, -v168, v172, v211
	v_fma_f32 v220, v168, v171, v212
	v_fma_f32 v171, v167, v171, v219
	v_fma_f32 v172, v167, v172, v220
	v_fma_f32 v219, -v170, v174, v213
	v_fma_f32 v220, v170, v173, v214
	v_fma_f32 v173, v169, v173, v219
	v_fma_f32 v174, v169, v174, v220
	v_mul_f32_e32 v183, v118, v38
	v_mul_f32_e32 v187, v118, v70
	v_fma_f32 v183, -v134, v70, v183
	v_fmac_f32_e32 v187, v134, v38
	v_mul_f32_e32 v184, v119, v39
	v_mul_f32_e32 v188, v119, v71
	v_fma_f32 v184, -v135, v71, v184
	v_fmac_f32_e32 v188, v135, v39
	v_mul_f32_e32 v185, v120, v40
	v_mul_f32_e32 v189, v120, v72
	v_fma_f32 v185, -v136, v72, v185
	v_fmac_f32_e32 v189, v136, v40
	v_mul_f32_e32 v186, v121, v41
	v_mul_f32_e32 v190, v121, v73
	v_fma_f32 v186, -v137, v73, v186
	v_fmac_f32_e32 v190, v137, v41
	v_fmac_f32_e32 v183, v122, v42
	v_fmac_f32_e32 v187, v122, v74
	v_fma_f32 v183, -v138, v74, v183
	v_fmac_f32_e32 v187, v138, v42
	v_fmac_f32_e32 v184, v123, v43
	v_fmac_f32_e32 v188, v123, v75
	v_fma_f32 v184, -v139, v75, v184
	v_fmac_f32_e32 v188, v139, v43
	v_fmac_f32_e32 v185, v124, v44
	v_fmac_f32_e32 v189, v124, v76
	v_fma_f32 v185, -v140, v76, v185
	v_fmac_f32_e32 v189, v140, v44
	v_fmac_f32_e32 v186, v125, v45
	v_fmac_f32_e32 v190, v125, v77
	v_fma_f32 v186, -v141, v77, v186
	v_fmac_f32_e32 v190, v141, v45
	v_fmac_f32_e32 v183, v126, v46
	v_fmac_f32_e32 v187, v126, v78
	v_fma_f32 v183, -v142, v78, v183
	v_fmac_f32_e32 v187, v142, v46
	v_fmac_f32_e32 v184, v127, v47
	v_fmac_f32_e32 v188, v127, v79
	v_fma_f32 v184, -v143, v79, v184
	v_fmac_f32_e32 v188, v143, v47
	v_fmac_f32_e32 v185, v128, v48
	v_fmac_f32_e32 v189, v128, v80
	v_fma_f32 v185, -v144, v80, v185
	v_fmac_f32_e32 v189, v144, v48
	v_fmac_f32_e32 v186, v129, v49
	v_fmac_f32_e32 v190, v129, v81
	v_fma_f32 v186, -v145, v81, v186
	v_fmac_f32_e32 v190, v145, v49
	v_fmac_f32_e32 v183, v130, v50
	v_fmac_f32_e32 v187, v130, v82
	v_fma_f32 v183, -v146, v82, v183
	v_fmac_f32_e32 v187, v146, v50
	v_fmac_f32_e32 v184, v131, v51
	v_fmac_f32_e32 v188, v131, v83
	v_fma_f32 v184, -v147, v83, v184
	v_fmac_f32_e32 v188, v147, v51
	v_fmac_f32_e32 v185, v132, v52
	v_fmac_f32_e32 v189, v132, v84
	v_fma_f32 v185, -v148, v84, v185
	v_fmac_f32_e32 v189, v148, v52
	v_fmac_f32_e32 v186, v133, v53
	v_fmac_f32_e32 v190, v133, v85
	v_fma_f32 v186, -v149, v85, v186
	v_fmac_f32_e32 v190, v149, v53
	s_waitcnt vmcnt(7)
	v_mfma_f32_32x32x16_bf16 v[22:37], v[192:195], v[6:9], 0
	v_mfma_f32_32x32x16_bf16 v[54:69], v[192:195], v[14:17], 0
	v_mfma_f32_32x32x16_bf16 v[38:53], v[192:195], v[10:13], 0
	v_mfma_f32_32x32x16_bf16 v[70:85], v[192:195], v[18:21], 0
	s_add_u32 s42, s32, 0x180000
	s_addc_u32 s43, s33, 0
	global_load_dwordx4 v[192:195], v210, s[42:43]
	v_add_f32_e32 v219, v175, v176
	v_add_f32_e32 v220, v177, v178
	v_add_f32_e32 v211, v219, v220
	v_add_f32_e32 v219, v179, v180
	v_add_f32_e32 v220, v181, v182
	v_add_f32_e32 v212, v219, v220
	v_add_f32_e32 v219, v183, v184
	v_add_f32_e32 v220, v185, v186
	v_add_f32_e32 v213, v219, v220
	v_add_f32_e32 v219, v187, v188
	v_add_f32_e32 v220, v189, v190
	v_add_f32_e32 v214, v219, v220
	ds_bpermute_b32 v215, v208, v211
	ds_bpermute_b32 v216, v208, v212
	ds_bpermute_b32 v217, v208, v213
	ds_bpermute_b32 v218, v208, v214
	v_mul_f32_e32 v175, v86, v22
	v_mul_f32_e32 v179, v86, v54
	v_fma_f32 v175, -v102, v54, v175
	v_fmac_f32_e32 v179, v102, v22
	v_mul_f32_e32 v176, v87, v23
	v_mul_f32_e32 v180, v87, v55
	v_fma_f32 v176, -v103, v55, v176
	v_fmac_f32_e32 v180, v103, v23
	v_mul_f32_e32 v177, v88, v24
	v_mul_f32_e32 v181, v88, v56
	v_fma_f32 v177, -v104, v56, v177
	v_fmac_f32_e32 v181, v104, v24
	v_mul_f32_e32 v178, v89, v25
	v_mul_f32_e32 v182, v89, v57
	v_fma_f32 v178, -v105, v57, v178
	v_fmac_f32_e32 v182, v105, v25
	v_fmac_f32_e32 v175, v90, v26
	v_fmac_f32_e32 v179, v90, v58
	v_fma_f32 v175, -v106, v58, v175
	v_fmac_f32_e32 v179, v106, v26
	v_fmac_f32_e32 v176, v91, v27
	v_fmac_f32_e32 v180, v91, v59
	v_fma_f32 v176, -v107, v59, v176
	v_fmac_f32_e32 v180, v107, v27
	v_fmac_f32_e32 v177, v92, v28
	v_fmac_f32_e32 v181, v92, v60
	v_fma_f32 v177, -v108, v60, v177
	v_fmac_f32_e32 v181, v108, v28
	v_fmac_f32_e32 v178, v93, v29
	v_fmac_f32_e32 v182, v93, v61
	v_fma_f32 v178, -v109, v61, v178
	v_fmac_f32_e32 v182, v109, v29
	v_fmac_f32_e32 v175, v94, v30
	v_fmac_f32_e32 v179, v94, v62
	v_fma_f32 v175, -v110, v62, v175
	v_fmac_f32_e32 v179, v110, v30
	v_fmac_f32_e32 v176, v95, v31
	v_fmac_f32_e32 v180, v95, v63
	v_fma_f32 v176, -v111, v63, v176
	v_fmac_f32_e32 v180, v111, v31
	v_fmac_f32_e32 v177, v96, v32
	v_fmac_f32_e32 v181, v96, v64
	v_fma_f32 v177, -v112, v64, v177
	v_fmac_f32_e32 v181, v112, v32
	v_fmac_f32_e32 v178, v97, v33
	v_fmac_f32_e32 v182, v97, v65
	v_fma_f32 v178, -v113, v65, v178
	v_fmac_f32_e32 v182, v113, v33
	v_fmac_f32_e32 v175, v98, v34
	v_fmac_f32_e32 v179, v98, v66
	v_fma_f32 v175, -v114, v66, v175
	v_fmac_f32_e32 v179, v114, v34
	v_fmac_f32_e32 v176, v99, v35
	v_fmac_f32_e32 v180, v99, v67
	v_fma_f32 v176, -v115, v67, v176
	v_fmac_f32_e32 v180, v115, v35
	v_fmac_f32_e32 v177, v100, v36
	v_fmac_f32_e32 v181, v100, v68
	v_fma_f32 v177, -v116, v68, v177
	v_fmac_f32_e32 v181, v116, v36
	v_fmac_f32_e32 v178, v101, v37
	v_fmac_f32_e32 v182, v101, v69
	v_fma_f32 v178, -v117, v69, v178
	v_fmac_f32_e32 v182, v117, v37
	s_waitcnt lgkmcnt(0)
	v_add_f32_e32 v211, v211, v215
	v_add_f32_e32 v212, v212, v216
	v_add_f32_e32 v213, v213, v217
	v_add_f32_e32 v214, v214, v218
	v_fma_f32 v219, -v168, v172, v211
	v_fma_f32 v220, v168, v171, v212
	v_fma_f32 v171, v167, v171, v219
	v_fma_f32 v172, v167, v172, v220
	v_fma_f32 v219, -v170, v174, v213
	v_fma_f32 v220, v170, v173, v214
	v_fma_f32 v173, v169, v173, v219
	v_fma_f32 v174, v169, v174, v220
	s_add_u32 s42, s38, 0x200
	s_addc_u32 s43, s39, 0
	s_mov_b64 exec, s[12:13]
	global_store_dword v209, v171, s[42:43]
	global_store_dword v209, v172, s[42:43] offset:256
	global_store_dword v209, v173, s[42:43] offset:128
	global_store_dword v209, v174, s[42:43] offset:384
	s_mov_b64 exec, -1
	v_mul_f32_e32 v183, v118, v38
	v_mul_f32_e32 v187, v118, v70
	v_fma_f32 v183, -v134, v70, v183
	v_fmac_f32_e32 v187, v134, v38
	v_mul_f32_e32 v184, v119, v39
	v_mul_f32_e32 v188, v119, v71
	v_fma_f32 v184, -v135, v71, v184
	v_fmac_f32_e32 v188, v135, v39
	v_mul_f32_e32 v185, v120, v40
	v_mul_f32_e32 v189, v120, v72
	v_fma_f32 v185, -v136, v72, v185
	v_fmac_f32_e32 v189, v136, v40
	v_mul_f32_e32 v186, v121, v41
	v_mul_f32_e32 v190, v121, v73
	v_fma_f32 v186, -v137, v73, v186
	v_fmac_f32_e32 v190, v137, v41
	v_fmac_f32_e32 v183, v122, v42
	v_fmac_f32_e32 v187, v122, v74
	v_fma_f32 v183, -v138, v74, v183
	v_fmac_f32_e32 v187, v138, v42
	v_fmac_f32_e32 v184, v123, v43
	v_fmac_f32_e32 v188, v123, v75
	v_fma_f32 v184, -v139, v75, v184
	v_fmac_f32_e32 v188, v139, v43
	v_fmac_f32_e32 v185, v124, v44
	v_fmac_f32_e32 v189, v124, v76
	v_fma_f32 v185, -v140, v76, v185
	v_fmac_f32_e32 v189, v140, v44
	v_fmac_f32_e32 v186, v125, v45
	v_fmac_f32_e32 v190, v125, v77
	v_fma_f32 v186, -v141, v77, v186
	v_fmac_f32_e32 v190, v141, v45
	v_fmac_f32_e32 v183, v126, v46
	v_fmac_f32_e32 v187, v126, v78
	v_fma_f32 v183, -v142, v78, v183
	v_fmac_f32_e32 v187, v142, v46
	v_fmac_f32_e32 v184, v127, v47
	v_fmac_f32_e32 v188, v127, v79
	v_fma_f32 v184, -v143, v79, v184
	v_fmac_f32_e32 v188, v143, v47
	v_fmac_f32_e32 v185, v128, v48
	v_fmac_f32_e32 v189, v128, v80
	v_fma_f32 v185, -v144, v80, v185
	v_fmac_f32_e32 v189, v144, v48
	v_fmac_f32_e32 v186, v129, v49
	v_fmac_f32_e32 v190, v129, v81
	v_fma_f32 v186, -v145, v81, v186
	v_fmac_f32_e32 v190, v145, v49
	v_fmac_f32_e32 v183, v130, v50
	v_fmac_f32_e32 v187, v130, v82
	v_fma_f32 v183, -v146, v82, v183
	v_fmac_f32_e32 v187, v146, v50
	v_fmac_f32_e32 v184, v131, v51
	v_fmac_f32_e32 v188, v131, v83
	v_fma_f32 v184, -v147, v83, v184
	v_fmac_f32_e32 v188, v147, v51
	v_fmac_f32_e32 v185, v132, v52
	v_fmac_f32_e32 v189, v132, v84
	v_fma_f32 v185, -v148, v84, v185
	v_fmac_f32_e32 v189, v148, v52
	v_fmac_f32_e32 v186, v133, v53
	v_fmac_f32_e32 v190, v133, v85
	v_fma_f32 v186, -v149, v85, v186
	v_fmac_f32_e32 v190, v149, v53
	s_waitcnt vmcnt(7)
	v_mfma_f32_32x32x16_bf16 v[22:37], v[196:199], v[6:9], 0
	v_mfma_f32_32x32x16_bf16 v[54:69], v[196:199], v[14:17], 0
	v_mfma_f32_32x32x16_bf16 v[38:53], v[196:199], v[10:13], 0
	v_mfma_f32_32x32x16_bf16 v[70:85], v[196:199], v[18:21], 0
	s_add_u32 s42, s32, 0x1a0000
	s_addc_u32 s43, s33, 0
	global_load_dwordx4 v[196:199], v210, s[42:43]
	v_add_f32_e32 v219, v175, v176
	v_add_f32_e32 v220, v177, v178
	v_add_f32_e32 v211, v219, v220
	v_add_f32_e32 v219, v179, v180
	v_add_f32_e32 v220, v181, v182
	v_add_f32_e32 v212, v219, v220
	v_add_f32_e32 v219, v183, v184
	v_add_f32_e32 v220, v185, v186
	v_add_f32_e32 v213, v219, v220
	v_add_f32_e32 v219, v187, v188
	v_add_f32_e32 v220, v189, v190
	v_add_f32_e32 v214, v219, v220
	ds_bpermute_b32 v215, v208, v211
	ds_bpermute_b32 v216, v208, v212
	ds_bpermute_b32 v217, v208, v213
	ds_bpermute_b32 v218, v208, v214
	v_mul_f32_e32 v175, v86, v22
	v_mul_f32_e32 v179, v86, v54
	v_fma_f32 v175, -v102, v54, v175
	v_fmac_f32_e32 v179, v102, v22
	v_mul_f32_e32 v176, v87, v23
	v_mul_f32_e32 v180, v87, v55
	v_fma_f32 v176, -v103, v55, v176
	v_fmac_f32_e32 v180, v103, v23
	v_mul_f32_e32 v177, v88, v24
	v_mul_f32_e32 v181, v88, v56
	v_fma_f32 v177, -v104, v56, v177
	v_fmac_f32_e32 v181, v104, v24
	v_mul_f32_e32 v178, v89, v25
	v_mul_f32_e32 v182, v89, v57
	v_fma_f32 v178, -v105, v57, v178
	v_fmac_f32_e32 v182, v105, v25
	v_fmac_f32_e32 v175, v90, v26
	v_fmac_f32_e32 v179, v90, v58
	v_fma_f32 v175, -v106, v58, v175
	v_fmac_f32_e32 v179, v106, v26
	v_fmac_f32_e32 v176, v91, v27
	v_fmac_f32_e32 v180, v91, v59
	v_fma_f32 v176, -v107, v59, v176
	v_fmac_f32_e32 v180, v107, v27
	v_fmac_f32_e32 v177, v92, v28
	v_fmac_f32_e32 v181, v92, v60
	v_fma_f32 v177, -v108, v60, v177
	v_fmac_f32_e32 v181, v108, v28
	v_fmac_f32_e32 v178, v93, v29
	v_fmac_f32_e32 v182, v93, v61
	v_fma_f32 v178, -v109, v61, v178
	v_fmac_f32_e32 v182, v109, v29
	v_fmac_f32_e32 v175, v94, v30
	v_fmac_f32_e32 v179, v94, v62
	v_fma_f32 v175, -v110, v62, v175
	v_fmac_f32_e32 v179, v110, v30
	v_fmac_f32_e32 v176, v95, v31
	v_fmac_f32_e32 v180, v95, v63
	v_fma_f32 v176, -v111, v63, v176
	v_fmac_f32_e32 v180, v111, v31
	v_fmac_f32_e32 v177, v96, v32
	v_fmac_f32_e32 v181, v96, v64
	v_fma_f32 v177, -v112, v64, v177
	v_fmac_f32_e32 v181, v112, v32
	v_fmac_f32_e32 v178, v97, v33
	v_fmac_f32_e32 v182, v97, v65
	v_fma_f32 v178, -v113, v65, v178
	v_fmac_f32_e32 v182, v113, v33
	v_fmac_f32_e32 v175, v98, v34
	v_fmac_f32_e32 v179, v98, v66
	v_fma_f32 v175, -v114, v66, v175
	v_fmac_f32_e32 v179, v114, v34
	v_fmac_f32_e32 v176, v99, v35
	v_fmac_f32_e32 v180, v99, v67
	v_fma_f32 v176, -v115, v67, v176
	v_fmac_f32_e32 v180, v115, v35
	v_fmac_f32_e32 v177, v100, v36
	v_fmac_f32_e32 v181, v100, v68
	v_fma_f32 v177, -v116, v68, v177
	v_fmac_f32_e32 v181, v116, v36
	v_fmac_f32_e32 v178, v101, v37
	v_fmac_f32_e32 v182, v101, v69
	v_fma_f32 v178, -v117, v69, v178
	v_fmac_f32_e32 v182, v117, v37
	s_waitcnt lgkmcnt(0)
	v_add_f32_e32 v211, v211, v215
	v_add_f32_e32 v212, v212, v216
	v_add_f32_e32 v213, v213, v217
	v_add_f32_e32 v214, v214, v218
	v_fma_f32 v219, -v168, v172, v211
	v_fma_f32 v220, v168, v171, v212
	v_fma_f32 v171, v167, v171, v219
	v_fma_f32 v172, v167, v172, v220
	v_fma_f32 v219, -v170, v174, v213
	v_fma_f32 v220, v170, v173, v214
	v_fma_f32 v173, v169, v173, v219
	v_fma_f32 v174, v169, v174, v220
	v_mul_f32_e32 v183, v118, v38
	v_mul_f32_e32 v187, v118, v70
	v_fma_f32 v183, -v134, v70, v183
	v_fmac_f32_e32 v187, v134, v38
	v_mul_f32_e32 v184, v119, v39
	v_mul_f32_e32 v188, v119, v71
	v_fma_f32 v184, -v135, v71, v184
	v_fmac_f32_e32 v188, v135, v39
	v_mul_f32_e32 v185, v120, v40
	v_mul_f32_e32 v189, v120, v72
	v_fma_f32 v185, -v136, v72, v185
	v_fmac_f32_e32 v189, v136, v40
	v_mul_f32_e32 v186, v121, v41
	v_mul_f32_e32 v190, v121, v73
	v_fma_f32 v186, -v137, v73, v186
	v_fmac_f32_e32 v190, v137, v41
	v_fmac_f32_e32 v183, v122, v42
	v_fmac_f32_e32 v187, v122, v74
	v_fma_f32 v183, -v138, v74, v183
	v_fmac_f32_e32 v187, v138, v42
	v_fmac_f32_e32 v184, v123, v43
	v_fmac_f32_e32 v188, v123, v75
	v_fma_f32 v184, -v139, v75, v184
	v_fmac_f32_e32 v188, v139, v43
	v_fmac_f32_e32 v185, v124, v44
	v_fmac_f32_e32 v189, v124, v76
	v_fma_f32 v185, -v140, v76, v185
	v_fmac_f32_e32 v189, v140, v44
	v_fmac_f32_e32 v186, v125, v45
	v_fmac_f32_e32 v190, v125, v77
	v_fma_f32 v186, -v141, v77, v186
	v_fmac_f32_e32 v190, v141, v45
	v_fmac_f32_e32 v183, v126, v46
	v_fmac_f32_e32 v187, v126, v78
	v_fma_f32 v183, -v142, v78, v183
	v_fmac_f32_e32 v187, v142, v46
	v_fmac_f32_e32 v184, v127, v47
	v_fmac_f32_e32 v188, v127, v79
	v_fma_f32 v184, -v143, v79, v184
	v_fmac_f32_e32 v188, v143, v47
	v_fmac_f32_e32 v185, v128, v48
	v_fmac_f32_e32 v189, v128, v80
	v_fma_f32 v185, -v144, v80, v185
	v_fmac_f32_e32 v189, v144, v48
	v_fmac_f32_e32 v186, v129, v49
	v_fmac_f32_e32 v190, v129, v81
	v_fma_f32 v186, -v145, v81, v186
	v_fmac_f32_e32 v190, v145, v49
	v_fmac_f32_e32 v183, v130, v50
	v_fmac_f32_e32 v187, v130, v82
	v_fma_f32 v183, -v146, v82, v183
	v_fmac_f32_e32 v187, v146, v50
	v_fmac_f32_e32 v184, v131, v51
	v_fmac_f32_e32 v188, v131, v83
	v_fma_f32 v184, -v147, v83, v184
	v_fmac_f32_e32 v188, v147, v51
	v_fmac_f32_e32 v185, v132, v52
	v_fmac_f32_e32 v189, v132, v84
	v_fma_f32 v185, -v148, v84, v185
	v_fmac_f32_e32 v189, v148, v52
	v_fmac_f32_e32 v186, v133, v53
	v_fmac_f32_e32 v190, v133, v85
	v_fma_f32 v186, -v149, v85, v186
	v_fmac_f32_e32 v190, v149, v53
	s_waitcnt vmcnt(7)
	v_mfma_f32_32x32x16_bf16 v[22:37], v[200:203], v[6:9], 0
	v_mfma_f32_32x32x16_bf16 v[54:69], v[200:203], v[14:17], 0
	v_mfma_f32_32x32x16_bf16 v[38:53], v[200:203], v[10:13], 0
	v_mfma_f32_32x32x16_bf16 v[70:85], v[200:203], v[18:21], 0
	s_add_u32 s42, s32, 0x1c0000
	s_addc_u32 s43, s33, 0
	global_load_dwordx4 v[200:203], v210, s[42:43]
	v_add_f32_e32 v219, v175, v176
	v_add_f32_e32 v220, v177, v178
	v_add_f32_e32 v211, v219, v220
	v_add_f32_e32 v219, v179, v180
	v_add_f32_e32 v220, v181, v182
	v_add_f32_e32 v212, v219, v220
	v_add_f32_e32 v219, v183, v184
	v_add_f32_e32 v220, v185, v186
	v_add_f32_e32 v213, v219, v220
	v_add_f32_e32 v219, v187, v188
	v_add_f32_e32 v220, v189, v190
	v_add_f32_e32 v214, v219, v220
	ds_bpermute_b32 v215, v208, v211
	ds_bpermute_b32 v216, v208, v212
	ds_bpermute_b32 v217, v208, v213
	ds_bpermute_b32 v218, v208, v214
	v_mul_f32_e32 v175, v86, v22
	v_mul_f32_e32 v179, v86, v54
	v_fma_f32 v175, -v102, v54, v175
	v_fmac_f32_e32 v179, v102, v22
	v_mul_f32_e32 v176, v87, v23
	v_mul_f32_e32 v180, v87, v55
	v_fma_f32 v176, -v103, v55, v176
	v_fmac_f32_e32 v180, v103, v23
	v_mul_f32_e32 v177, v88, v24
	v_mul_f32_e32 v181, v88, v56
	v_fma_f32 v177, -v104, v56, v177
	v_fmac_f32_e32 v181, v104, v24
	v_mul_f32_e32 v178, v89, v25
	v_mul_f32_e32 v182, v89, v57
	v_fma_f32 v178, -v105, v57, v178
	v_fmac_f32_e32 v182, v105, v25
	v_fmac_f32_e32 v175, v90, v26
	v_fmac_f32_e32 v179, v90, v58
	v_fma_f32 v175, -v106, v58, v175
	v_fmac_f32_e32 v179, v106, v26
	v_fmac_f32_e32 v176, v91, v27
	v_fmac_f32_e32 v180, v91, v59
	v_fma_f32 v176, -v107, v59, v176
	v_fmac_f32_e32 v180, v107, v27
	v_fmac_f32_e32 v177, v92, v28
	v_fmac_f32_e32 v181, v92, v60
	v_fma_f32 v177, -v108, v60, v177
	v_fmac_f32_e32 v181, v108, v28
	v_fmac_f32_e32 v178, v93, v29
	v_fmac_f32_e32 v182, v93, v61
	v_fma_f32 v178, -v109, v61, v178
	v_fmac_f32_e32 v182, v109, v29
	v_fmac_f32_e32 v175, v94, v30
	v_fmac_f32_e32 v179, v94, v62
	v_fma_f32 v175, -v110, v62, v175
	v_fmac_f32_e32 v179, v110, v30
	v_fmac_f32_e32 v176, v95, v31
	v_fmac_f32_e32 v180, v95, v63
	v_fma_f32 v176, -v111, v63, v176
	v_fmac_f32_e32 v180, v111, v31
	v_fmac_f32_e32 v177, v96, v32
	v_fmac_f32_e32 v181, v96, v64
	v_fma_f32 v177, -v112, v64, v177
	v_fmac_f32_e32 v181, v112, v32
	v_fmac_f32_e32 v178, v97, v33
	v_fmac_f32_e32 v182, v97, v65
	v_fma_f32 v178, -v113, v65, v178
	v_fmac_f32_e32 v182, v113, v33
	v_fmac_f32_e32 v175, v98, v34
	v_fmac_f32_e32 v179, v98, v66
	v_fma_f32 v175, -v114, v66, v175
	v_fmac_f32_e32 v179, v114, v34
	v_fmac_f32_e32 v176, v99, v35
	v_fmac_f32_e32 v180, v99, v67
	v_fma_f32 v176, -v115, v67, v176
	v_fmac_f32_e32 v180, v115, v35
	v_fmac_f32_e32 v177, v100, v36
	v_fmac_f32_e32 v181, v100, v68
	v_fma_f32 v177, -v116, v68, v177
	v_fmac_f32_e32 v181, v116, v36
	v_fmac_f32_e32 v178, v101, v37
	v_fmac_f32_e32 v182, v101, v69
	v_fma_f32 v178, -v117, v69, v178
	v_fmac_f32_e32 v182, v117, v37
	s_waitcnt lgkmcnt(0)
	v_add_f32_e32 v211, v211, v215
	v_add_f32_e32 v212, v212, v216
	v_add_f32_e32 v213, v213, v217
	v_add_f32_e32 v214, v214, v218
	v_fma_f32 v219, -v168, v172, v211
	v_fma_f32 v220, v168, v171, v212
	v_fma_f32 v171, v167, v171, v219
	v_fma_f32 v172, v167, v172, v220
	v_fma_f32 v219, -v170, v174, v213
	v_fma_f32 v220, v170, v173, v214
	v_fma_f32 v173, v169, v173, v219
	v_fma_f32 v174, v169, v174, v220
	v_mul_f32_e32 v183, v118, v38
	v_mul_f32_e32 v187, v118, v70
	v_fma_f32 v183, -v134, v70, v183
	v_fmac_f32_e32 v187, v134, v38
	v_mul_f32_e32 v184, v119, v39
	v_mul_f32_e32 v188, v119, v71
	v_fma_f32 v184, -v135, v71, v184
	v_fmac_f32_e32 v188, v135, v39
	v_mul_f32_e32 v185, v120, v40
	v_mul_f32_e32 v189, v120, v72
	v_fma_f32 v185, -v136, v72, v185
	v_fmac_f32_e32 v189, v136, v40
	v_mul_f32_e32 v186, v121, v41
	v_mul_f32_e32 v190, v121, v73
	v_fma_f32 v186, -v137, v73, v186
	v_fmac_f32_e32 v190, v137, v41
	v_fmac_f32_e32 v183, v122, v42
	v_fmac_f32_e32 v187, v122, v74
	v_fma_f32 v183, -v138, v74, v183
	v_fmac_f32_e32 v187, v138, v42
	v_fmac_f32_e32 v184, v123, v43
	v_fmac_f32_e32 v188, v123, v75
	v_fma_f32 v184, -v139, v75, v184
	v_fmac_f32_e32 v188, v139, v43
	v_fmac_f32_e32 v185, v124, v44
	v_fmac_f32_e32 v189, v124, v76
	v_fma_f32 v185, -v140, v76, v185
	v_fmac_f32_e32 v189, v140, v44
	v_fmac_f32_e32 v186, v125, v45
	v_fmac_f32_e32 v190, v125, v77
	v_fma_f32 v186, -v141, v77, v186
	v_fmac_f32_e32 v190, v141, v45
	v_fmac_f32_e32 v183, v126, v46
	v_fmac_f32_e32 v187, v126, v78
	v_fma_f32 v183, -v142, v78, v183
	v_fmac_f32_e32 v187, v142, v46
	v_fmac_f32_e32 v184, v127, v47
	v_fmac_f32_e32 v188, v127, v79
	v_fma_f32 v184, -v143, v79, v184
	v_fmac_f32_e32 v188, v143, v47
	v_fmac_f32_e32 v185, v128, v48
	v_fmac_f32_e32 v189, v128, v80
	v_fma_f32 v185, -v144, v80, v185
	v_fmac_f32_e32 v189, v144, v48
	v_fmac_f32_e32 v186, v129, v49
	v_fmac_f32_e32 v190, v129, v81
	v_fma_f32 v186, -v145, v81, v186
	v_fmac_f32_e32 v190, v145, v49
	v_fmac_f32_e32 v183, v130, v50
	v_fmac_f32_e32 v187, v130, v82
	v_fma_f32 v183, -v146, v82, v183
	v_fmac_f32_e32 v187, v146, v50
	v_fmac_f32_e32 v184, v131, v51
	v_fmac_f32_e32 v188, v131, v83
	v_fma_f32 v184, -v147, v83, v184
	v_fmac_f32_e32 v188, v147, v51
	v_fmac_f32_e32 v185, v132, v52
	v_fmac_f32_e32 v189, v132, v84
	v_fma_f32 v185, -v148, v84, v185
	v_fmac_f32_e32 v189, v148, v52
	v_fmac_f32_e32 v186, v133, v53
	v_fmac_f32_e32 v190, v133, v85
	v_fma_f32 v186, -v149, v85, v186
	v_fmac_f32_e32 v190, v149, v53
	s_waitcnt vmcnt(7)
	v_mfma_f32_32x32x16_bf16 v[22:37], v[204:207], v[6:9], 0
	v_mfma_f32_32x32x16_bf16 v[54:69], v[204:207], v[14:17], 0
	v_mfma_f32_32x32x16_bf16 v[38:53], v[204:207], v[10:13], 0
	v_mfma_f32_32x32x16_bf16 v[70:85], v[204:207], v[18:21], 0
	s_add_u32 s42, s32, 0x1e0000
	s_addc_u32 s43, s33, 0
	global_load_dwordx4 v[204:207], v210, s[42:43]
	v_add_f32_e32 v219, v175, v176
	v_add_f32_e32 v220, v177, v178
	v_add_f32_e32 v211, v219, v220
	v_add_f32_e32 v219, v179, v180
	v_add_f32_e32 v220, v181, v182
	v_add_f32_e32 v212, v219, v220
	v_add_f32_e32 v219, v183, v184
	v_add_f32_e32 v220, v185, v186
	v_add_f32_e32 v213, v219, v220
	v_add_f32_e32 v219, v187, v188
	v_add_f32_e32 v220, v189, v190
	v_add_f32_e32 v214, v219, v220
	ds_bpermute_b32 v215, v208, v211
	ds_bpermute_b32 v216, v208, v212
	ds_bpermute_b32 v217, v208, v213
	ds_bpermute_b32 v218, v208, v214
	v_mul_f32_e32 v175, v86, v22
	v_mul_f32_e32 v179, v86, v54
	v_fma_f32 v175, -v102, v54, v175
	v_fmac_f32_e32 v179, v102, v22
	v_mul_f32_e32 v176, v87, v23
	v_mul_f32_e32 v180, v87, v55
	v_fma_f32 v176, -v103, v55, v176
	v_fmac_f32_e32 v180, v103, v23
	v_mul_f32_e32 v177, v88, v24
	v_mul_f32_e32 v181, v88, v56
	v_fma_f32 v177, -v104, v56, v177
	v_fmac_f32_e32 v181, v104, v24
	v_mul_f32_e32 v178, v89, v25
	v_mul_f32_e32 v182, v89, v57
	v_fma_f32 v178, -v105, v57, v178
	v_fmac_f32_e32 v182, v105, v25
	v_fmac_f32_e32 v175, v90, v26
	v_fmac_f32_e32 v179, v90, v58
	v_fma_f32 v175, -v106, v58, v175
	v_fmac_f32_e32 v179, v106, v26
	v_fmac_f32_e32 v176, v91, v27
	v_fmac_f32_e32 v180, v91, v59
	v_fma_f32 v176, -v107, v59, v176
	v_fmac_f32_e32 v180, v107, v27
	v_fmac_f32_e32 v177, v92, v28
	v_fmac_f32_e32 v181, v92, v60
	v_fma_f32 v177, -v108, v60, v177
	v_fmac_f32_e32 v181, v108, v28
	v_fmac_f32_e32 v178, v93, v29
	v_fmac_f32_e32 v182, v93, v61
	v_fma_f32 v178, -v109, v61, v178
	v_fmac_f32_e32 v182, v109, v29
	v_fmac_f32_e32 v175, v94, v30
	v_fmac_f32_e32 v179, v94, v62
	v_fma_f32 v175, -v110, v62, v175
	v_fmac_f32_e32 v179, v110, v30
	v_fmac_f32_e32 v176, v95, v31
	v_fmac_f32_e32 v180, v95, v63
	v_fma_f32 v176, -v111, v63, v176
	v_fmac_f32_e32 v180, v111, v31
	v_fmac_f32_e32 v177, v96, v32
	v_fmac_f32_e32 v181, v96, v64
	v_fma_f32 v177, -v112, v64, v177
	v_fmac_f32_e32 v181, v112, v32
	v_fmac_f32_e32 v178, v97, v33
	v_fmac_f32_e32 v182, v97, v65
	v_fma_f32 v178, -v113, v65, v178
	v_fmac_f32_e32 v182, v113, v33
	v_fmac_f32_e32 v175, v98, v34
	v_fmac_f32_e32 v179, v98, v66
	v_fma_f32 v175, -v114, v66, v175
	v_fmac_f32_e32 v179, v114, v34
	v_fmac_f32_e32 v176, v99, v35
	v_fmac_f32_e32 v180, v99, v67
	v_fma_f32 v176, -v115, v67, v176
	v_fmac_f32_e32 v180, v115, v35
	v_fmac_f32_e32 v177, v100, v36
	v_fmac_f32_e32 v181, v100, v68
	v_fma_f32 v177, -v116, v68, v177
	v_fmac_f32_e32 v181, v116, v36
	v_fmac_f32_e32 v178, v101, v37
	v_fmac_f32_e32 v182, v101, v69
	v_fma_f32 v178, -v117, v69, v178
	v_fmac_f32_e32 v182, v117, v37
	s_waitcnt lgkmcnt(0)
	v_add_f32_e32 v211, v211, v215
	v_add_f32_e32 v212, v212, v216
	v_add_f32_e32 v213, v213, v217
	v_add_f32_e32 v214, v214, v218
	v_fma_f32 v219, -v168, v172, v211
	v_fma_f32 v220, v168, v171, v212
	v_fma_f32 v171, v167, v171, v219
	v_fma_f32 v172, v167, v172, v220
	v_fma_f32 v219, -v170, v174, v213
	v_fma_f32 v220, v170, v173, v214
	v_fma_f32 v173, v169, v173, v219
	v_fma_f32 v174, v169, v174, v220
	v_mul_f32_e32 v183, v118, v38
	v_mul_f32_e32 v187, v118, v70
	v_fma_f32 v183, -v134, v70, v183
	v_fmac_f32_e32 v187, v134, v38
	v_mul_f32_e32 v184, v119, v39
	v_mul_f32_e32 v188, v119, v71
	v_fma_f32 v184, -v135, v71, v184
	v_fmac_f32_e32 v188, v135, v39
	v_mul_f32_e32 v185, v120, v40
	v_mul_f32_e32 v189, v120, v72
	v_fma_f32 v185, -v136, v72, v185
	v_fmac_f32_e32 v189, v136, v40
	v_mul_f32_e32 v186, v121, v41
	v_mul_f32_e32 v190, v121, v73
	v_fma_f32 v186, -v137, v73, v186
	v_fmac_f32_e32 v190, v137, v41
	v_fmac_f32_e32 v183, v122, v42
	v_fmac_f32_e32 v187, v122, v74
	v_fma_f32 v183, -v138, v74, v183
	v_fmac_f32_e32 v187, v138, v42
	v_fmac_f32_e32 v184, v123, v43
	v_fmac_f32_e32 v188, v123, v75
	v_fma_f32 v184, -v139, v75, v184
	v_fmac_f32_e32 v188, v139, v43
	v_fmac_f32_e32 v185, v124, v44
	v_fmac_f32_e32 v189, v124, v76
	v_fma_f32 v185, -v140, v76, v185
	v_fmac_f32_e32 v189, v140, v44
	v_fmac_f32_e32 v186, v125, v45
	v_fmac_f32_e32 v190, v125, v77
	v_fma_f32 v186, -v141, v77, v186
	v_fmac_f32_e32 v190, v141, v45
	v_fmac_f32_e32 v183, v126, v46
	v_fmac_f32_e32 v187, v126, v78
	v_fma_f32 v183, -v142, v78, v183
	v_fmac_f32_e32 v187, v142, v46
	v_fmac_f32_e32 v184, v127, v47
	v_fmac_f32_e32 v188, v127, v79
	v_fma_f32 v184, -v143, v79, v184
	v_fmac_f32_e32 v188, v143, v47
	v_fmac_f32_e32 v185, v128, v48
	v_fmac_f32_e32 v189, v128, v80
	v_fma_f32 v185, -v144, v80, v185
	v_fmac_f32_e32 v189, v144, v48
	v_fmac_f32_e32 v186, v129, v49
	v_fmac_f32_e32 v190, v129, v81
	v_fma_f32 v186, -v145, v81, v186
	v_fmac_f32_e32 v190, v145, v49
	v_fmac_f32_e32 v183, v130, v50
	v_fmac_f32_e32 v187, v130, v82
	v_fma_f32 v183, -v146, v82, v183
	v_fmac_f32_e32 v187, v146, v50
	v_fmac_f32_e32 v184, v131, v51
	v_fmac_f32_e32 v188, v131, v83
	v_fma_f32 v184, -v147, v83, v184
	v_fmac_f32_e32 v188, v147, v51
	v_fmac_f32_e32 v185, v132, v52
	v_fmac_f32_e32 v189, v132, v84
	v_fma_f32 v185, -v148, v84, v185
	v_fmac_f32_e32 v189, v148, v52
	v_fmac_f32_e32 v186, v133, v53
	v_fmac_f32_e32 v190, v133, v85
	v_fma_f32 v186, -v149, v85, v186
	v_fmac_f32_e32 v190, v149, v53
	s_waitcnt vmcnt(7)
	v_mfma_f32_32x32x16_bf16 v[22:37], v[192:195], v[6:9], 0
	v_mfma_f32_32x32x16_bf16 v[54:69], v[192:195], v[14:17], 0
	v_mfma_f32_32x32x16_bf16 v[38:53], v[192:195], v[10:13], 0
	v_mfma_f32_32x32x16_bf16 v[70:85], v[192:195], v[18:21], 0
	v_add_f32_e32 v219, v175, v176
	v_add_f32_e32 v220, v177, v178
	v_add_f32_e32 v211, v219, v220
	v_add_f32_e32 v219, v179, v180
	v_add_f32_e32 v220, v181, v182
	v_add_f32_e32 v212, v219, v220
	v_add_f32_e32 v219, v183, v184
	v_add_f32_e32 v220, v185, v186
	v_add_f32_e32 v213, v219, v220
	v_add_f32_e32 v219, v187, v188
	v_add_f32_e32 v220, v189, v190
	v_add_f32_e32 v214, v219, v220
	ds_bpermute_b32 v215, v208, v211
	ds_bpermute_b32 v216, v208, v212
	ds_bpermute_b32 v217, v208, v213
	ds_bpermute_b32 v218, v208, v214
	v_mul_f32_e32 v175, v86, v22
	v_mul_f32_e32 v179, v86, v54
	v_fma_f32 v175, -v102, v54, v175
	v_fmac_f32_e32 v179, v102, v22
	v_mul_f32_e32 v176, v87, v23
	v_mul_f32_e32 v180, v87, v55
	v_fma_f32 v176, -v103, v55, v176
	v_fmac_f32_e32 v180, v103, v23
	v_mul_f32_e32 v177, v88, v24
	v_mul_f32_e32 v181, v88, v56
	v_fma_f32 v177, -v104, v56, v177
	v_fmac_f32_e32 v181, v104, v24
	v_mul_f32_e32 v178, v89, v25
	v_mul_f32_e32 v182, v89, v57
	v_fma_f32 v178, -v105, v57, v178
	v_fmac_f32_e32 v182, v105, v25
	v_fmac_f32_e32 v175, v90, v26
	v_fmac_f32_e32 v179, v90, v58
	v_fma_f32 v175, -v106, v58, v175
	v_fmac_f32_e32 v179, v106, v26
	v_fmac_f32_e32 v176, v91, v27
	v_fmac_f32_e32 v180, v91, v59
	v_fma_f32 v176, -v107, v59, v176
	v_fmac_f32_e32 v180, v107, v27
	v_fmac_f32_e32 v177, v92, v28
	v_fmac_f32_e32 v181, v92, v60
	v_fma_f32 v177, -v108, v60, v177
	v_fmac_f32_e32 v181, v108, v28
	v_fmac_f32_e32 v178, v93, v29
	v_fmac_f32_e32 v182, v93, v61
	v_fma_f32 v178, -v109, v61, v178
	v_fmac_f32_e32 v182, v109, v29
	v_fmac_f32_e32 v175, v94, v30
	v_fmac_f32_e32 v179, v94, v62
	v_fma_f32 v175, -v110, v62, v175
	v_fmac_f32_e32 v179, v110, v30
	v_fmac_f32_e32 v176, v95, v31
	v_fmac_f32_e32 v180, v95, v63
	v_fma_f32 v176, -v111, v63, v176
	v_fmac_f32_e32 v180, v111, v31
	v_fmac_f32_e32 v177, v96, v32
	v_fmac_f32_e32 v181, v96, v64
	v_fma_f32 v177, -v112, v64, v177
	v_fmac_f32_e32 v181, v112, v32
	v_fmac_f32_e32 v178, v97, v33
	v_fmac_f32_e32 v182, v97, v65
	v_fma_f32 v178, -v113, v65, v178
	v_fmac_f32_e32 v182, v113, v33
	v_fmac_f32_e32 v175, v98, v34
	v_fmac_f32_e32 v179, v98, v66
	v_fma_f32 v175, -v114, v66, v175
	v_fmac_f32_e32 v179, v114, v34
	v_fmac_f32_e32 v176, v99, v35
	v_fmac_f32_e32 v180, v99, v67
	v_fma_f32 v176, -v115, v67, v176
	v_fmac_f32_e32 v180, v115, v35
	v_fmac_f32_e32 v177, v100, v36
	v_fmac_f32_e32 v181, v100, v68
	v_fma_f32 v177, -v116, v68, v177
	v_fmac_f32_e32 v181, v116, v36
	v_fmac_f32_e32 v178, v101, v37
	v_fmac_f32_e32 v182, v101, v69
	v_fma_f32 v178, -v117, v69, v178
	v_fmac_f32_e32 v182, v117, v37
	s_waitcnt lgkmcnt(0)
	v_add_f32_e32 v211, v211, v215
	v_add_f32_e32 v212, v212, v216
	v_add_f32_e32 v213, v213, v217
	v_add_f32_e32 v214, v214, v218
	v_fma_f32 v219, -v168, v172, v211
	v_fma_f32 v220, v168, v171, v212
	v_fma_f32 v171, v167, v171, v219
	v_fma_f32 v172, v167, v172, v220
	v_fma_f32 v219, -v170, v174, v213
	v_fma_f32 v220, v170, v173, v214
	v_fma_f32 v173, v169, v173, v219
	v_fma_f32 v174, v169, v174, v220
	s_add_u32 s42, s38, 0x400
	s_addc_u32 s43, s39, 0
	s_mov_b64 exec, s[12:13]
	global_store_dword v209, v171, s[42:43]
	global_store_dword v209, v172, s[42:43] offset:256
	global_store_dword v209, v173, s[42:43] offset:128
	global_store_dword v209, v174, s[42:43] offset:384
	s_mov_b64 exec, -1
	v_mul_f32_e32 v183, v118, v38
	v_mul_f32_e32 v187, v118, v70
	v_fma_f32 v183, -v134, v70, v183
	v_fmac_f32_e32 v187, v134, v38
	v_mul_f32_e32 v184, v119, v39
	v_mul_f32_e32 v188, v119, v71
	v_fma_f32 v184, -v135, v71, v184
	v_fmac_f32_e32 v188, v135, v39
	v_mul_f32_e32 v185, v120, v40
	v_mul_f32_e32 v189, v120, v72
	v_fma_f32 v185, -v136, v72, v185
	v_fmac_f32_e32 v189, v136, v40
	v_mul_f32_e32 v186, v121, v41
	v_mul_f32_e32 v190, v121, v73
	v_fma_f32 v186, -v137, v73, v186
	v_fmac_f32_e32 v190, v137, v41
	v_fmac_f32_e32 v183, v122, v42
	v_fmac_f32_e32 v187, v122, v74
	v_fma_f32 v183, -v138, v74, v183
	v_fmac_f32_e32 v187, v138, v42
	v_fmac_f32_e32 v184, v123, v43
	v_fmac_f32_e32 v188, v123, v75
	v_fma_f32 v184, -v139, v75, v184
	v_fmac_f32_e32 v188, v139, v43
	v_fmac_f32_e32 v185, v124, v44
	v_fmac_f32_e32 v189, v124, v76
	v_fma_f32 v185, -v140, v76, v185
	v_fmac_f32_e32 v189, v140, v44
	v_fmac_f32_e32 v186, v125, v45
	v_fmac_f32_e32 v190, v125, v77
	v_fma_f32 v186, -v141, v77, v186
	v_fmac_f32_e32 v190, v141, v45
	v_fmac_f32_e32 v183, v126, v46
	v_fmac_f32_e32 v187, v126, v78
	v_fma_f32 v183, -v142, v78, v183
	v_fmac_f32_e32 v187, v142, v46
	v_fmac_f32_e32 v184, v127, v47
	v_fmac_f32_e32 v188, v127, v79
	v_fma_f32 v184, -v143, v79, v184
	v_fmac_f32_e32 v188, v143, v47
	v_fmac_f32_e32 v185, v128, v48
	v_fmac_f32_e32 v189, v128, v80
	v_fma_f32 v185, -v144, v80, v185
	v_fmac_f32_e32 v189, v144, v48
	v_fmac_f32_e32 v186, v129, v49
	v_fmac_f32_e32 v190, v129, v81
	v_fma_f32 v186, -v145, v81, v186
	v_fmac_f32_e32 v190, v145, v49
	v_fmac_f32_e32 v183, v130, v50
	v_fmac_f32_e32 v187, v130, v82
	v_fma_f32 v183, -v146, v82, v183
	v_fmac_f32_e32 v187, v146, v50
	v_fmac_f32_e32 v184, v131, v51
	v_fmac_f32_e32 v188, v131, v83
	v_fma_f32 v184, -v147, v83, v184
	v_fmac_f32_e32 v188, v147, v51
	v_fmac_f32_e32 v185, v132, v52
	v_fmac_f32_e32 v189, v132, v84
	v_fma_f32 v185, -v148, v84, v185
	v_fmac_f32_e32 v189, v148, v52
	v_fmac_f32_e32 v186, v133, v53
	v_fmac_f32_e32 v190, v133, v85
	v_fma_f32 v186, -v149, v85, v186
	v_fmac_f32_e32 v190, v149, v53
	s_waitcnt vmcnt(6)
	v_mfma_f32_32x32x16_bf16 v[22:37], v[196:199], v[6:9], 0
	v_mfma_f32_32x32x16_bf16 v[54:69], v[196:199], v[14:17], 0
	v_mfma_f32_32x32x16_bf16 v[38:53], v[196:199], v[10:13], 0
	v_mfma_f32_32x32x16_bf16 v[70:85], v[196:199], v[18:21], 0
	v_add_f32_e32 v219, v175, v176
	v_add_f32_e32 v220, v177, v178
	v_add_f32_e32 v211, v219, v220
	v_add_f32_e32 v219, v179, v180
	v_add_f32_e32 v220, v181, v182
	v_add_f32_e32 v212, v219, v220
	v_add_f32_e32 v219, v183, v184
	v_add_f32_e32 v220, v185, v186
	v_add_f32_e32 v213, v219, v220
	v_add_f32_e32 v219, v187, v188
	v_add_f32_e32 v220, v189, v190
	v_add_f32_e32 v214, v219, v220
	ds_bpermute_b32 v215, v208, v211
	ds_bpermute_b32 v216, v208, v212
	ds_bpermute_b32 v217, v208, v213
	ds_bpermute_b32 v218, v208, v214
	v_mul_f32_e32 v175, v86, v22
	v_mul_f32_e32 v179, v86, v54
	v_fma_f32 v175, -v102, v54, v175
	v_fmac_f32_e32 v179, v102, v22
	v_mul_f32_e32 v176, v87, v23
	v_mul_f32_e32 v180, v87, v55
	v_fma_f32 v176, -v103, v55, v176
	v_fmac_f32_e32 v180, v103, v23
	v_mul_f32_e32 v177, v88, v24
	v_mul_f32_e32 v181, v88, v56
	v_fma_f32 v177, -v104, v56, v177
	v_fmac_f32_e32 v181, v104, v24
	v_mul_f32_e32 v178, v89, v25
	v_mul_f32_e32 v182, v89, v57
	v_fma_f32 v178, -v105, v57, v178
	v_fmac_f32_e32 v182, v105, v25
	v_fmac_f32_e32 v175, v90, v26
	v_fmac_f32_e32 v179, v90, v58
	v_fma_f32 v175, -v106, v58, v175
	v_fmac_f32_e32 v179, v106, v26
	v_fmac_f32_e32 v176, v91, v27
	v_fmac_f32_e32 v180, v91, v59
	v_fma_f32 v176, -v107, v59, v176
	v_fmac_f32_e32 v180, v107, v27
	v_fmac_f32_e32 v177, v92, v28
	v_fmac_f32_e32 v181, v92, v60
	v_fma_f32 v177, -v108, v60, v177
	v_fmac_f32_e32 v181, v108, v28
	v_fmac_f32_e32 v178, v93, v29
	v_fmac_f32_e32 v182, v93, v61
	v_fma_f32 v178, -v109, v61, v178
	v_fmac_f32_e32 v182, v109, v29
	v_fmac_f32_e32 v175, v94, v30
	v_fmac_f32_e32 v179, v94, v62
	v_fma_f32 v175, -v110, v62, v175
	v_fmac_f32_e32 v179, v110, v30
	v_fmac_f32_e32 v176, v95, v31
	v_fmac_f32_e32 v180, v95, v63
	v_fma_f32 v176, -v111, v63, v176
	v_fmac_f32_e32 v180, v111, v31
	v_fmac_f32_e32 v177, v96, v32
	v_fmac_f32_e32 v181, v96, v64
	v_fma_f32 v177, -v112, v64, v177
	v_fmac_f32_e32 v181, v112, v32
	v_fmac_f32_e32 v178, v97, v33
	v_fmac_f32_e32 v182, v97, v65
	v_fma_f32 v178, -v113, v65, v178
	v_fmac_f32_e32 v182, v113, v33
	v_fmac_f32_e32 v175, v98, v34
	v_fmac_f32_e32 v179, v98, v66
	v_fma_f32 v175, -v114, v66, v175
	v_fmac_f32_e32 v179, v114, v34
	v_fmac_f32_e32 v176, v99, v35
	v_fmac_f32_e32 v180, v99, v67
	v_fma_f32 v176, -v115, v67, v176
	v_fmac_f32_e32 v180, v115, v35
	v_fmac_f32_e32 v177, v100, v36
	v_fmac_f32_e32 v181, v100, v68
	v_fma_f32 v177, -v116, v68, v177
	v_fmac_f32_e32 v181, v116, v36
	v_fmac_f32_e32 v178, v101, v37
	v_fmac_f32_e32 v182, v101, v69
	v_fma_f32 v178, -v117, v69, v178
	v_fmac_f32_e32 v182, v117, v37
	s_waitcnt lgkmcnt(0)
	v_add_f32_e32 v211, v211, v215
	v_add_f32_e32 v212, v212, v216
	v_add_f32_e32 v213, v213, v217
	v_add_f32_e32 v214, v214, v218
	v_fma_f32 v219, -v168, v172, v211
	v_fma_f32 v220, v168, v171, v212
	v_fma_f32 v171, v167, v171, v219
	v_fma_f32 v172, v167, v172, v220
	v_fma_f32 v219, -v170, v174, v213
	v_fma_f32 v220, v170, v173, v214
	v_fma_f32 v173, v169, v173, v219
	v_fma_f32 v174, v169, v174, v220
	v_mul_f32_e32 v183, v118, v38
	v_mul_f32_e32 v187, v118, v70
	v_fma_f32 v183, -v134, v70, v183
	v_fmac_f32_e32 v187, v134, v38
	v_mul_f32_e32 v184, v119, v39
	v_mul_f32_e32 v188, v119, v71
	v_fma_f32 v184, -v135, v71, v184
	v_fmac_f32_e32 v188, v135, v39
	v_mul_f32_e32 v185, v120, v40
	v_mul_f32_e32 v189, v120, v72
	v_fma_f32 v185, -v136, v72, v185
	v_fmac_f32_e32 v189, v136, v40
	v_mul_f32_e32 v186, v121, v41
	v_mul_f32_e32 v190, v121, v73
	v_fma_f32 v186, -v137, v73, v186
	v_fmac_f32_e32 v190, v137, v41
	v_fmac_f32_e32 v183, v122, v42
	v_fmac_f32_e32 v187, v122, v74
	v_fma_f32 v183, -v138, v74, v183
	v_fmac_f32_e32 v187, v138, v42
	v_fmac_f32_e32 v184, v123, v43
	v_fmac_f32_e32 v188, v123, v75
	v_fma_f32 v184, -v139, v75, v184
	v_fmac_f32_e32 v188, v139, v43
	v_fmac_f32_e32 v185, v124, v44
	v_fmac_f32_e32 v189, v124, v76
	v_fma_f32 v185, -v140, v76, v185
	v_fmac_f32_e32 v189, v140, v44
	v_fmac_f32_e32 v186, v125, v45
	v_fmac_f32_e32 v190, v125, v77
	v_fma_f32 v186, -v141, v77, v186
	v_fmac_f32_e32 v190, v141, v45
	v_fmac_f32_e32 v183, v126, v46
	v_fmac_f32_e32 v187, v126, v78
	v_fma_f32 v183, -v142, v78, v183
	v_fmac_f32_e32 v187, v142, v46
	v_fmac_f32_e32 v184, v127, v47
	v_fmac_f32_e32 v188, v127, v79
	v_fma_f32 v184, -v143, v79, v184
	v_fmac_f32_e32 v188, v143, v47
	v_fmac_f32_e32 v185, v128, v48
	v_fmac_f32_e32 v189, v128, v80
	v_fma_f32 v185, -v144, v80, v185
	v_fmac_f32_e32 v189, v144, v48
	v_fmac_f32_e32 v186, v129, v49
	v_fmac_f32_e32 v190, v129, v81
	v_fma_f32 v186, -v145, v81, v186
	v_fmac_f32_e32 v190, v145, v49
	v_fmac_f32_e32 v183, v130, v50
	v_fmac_f32_e32 v187, v130, v82
	v_fma_f32 v183, -v146, v82, v183
	v_fmac_f32_e32 v187, v146, v50
	v_fmac_f32_e32 v184, v131, v51
	v_fmac_f32_e32 v188, v131, v83
	v_fma_f32 v184, -v147, v83, v184
	v_fmac_f32_e32 v188, v147, v51
	v_fmac_f32_e32 v185, v132, v52
	v_fmac_f32_e32 v189, v132, v84
	v_fma_f32 v185, -v148, v84, v185
	v_fmac_f32_e32 v189, v148, v52
	v_fmac_f32_e32 v186, v133, v53
	v_fmac_f32_e32 v190, v133, v85
	v_fma_f32 v186, -v149, v85, v186
	v_fmac_f32_e32 v190, v149, v53
	s_waitcnt vmcnt(5)
	v_mfma_f32_32x32x16_bf16 v[22:37], v[200:203], v[6:9], 0
	v_mfma_f32_32x32x16_bf16 v[54:69], v[200:203], v[14:17], 0
	v_mfma_f32_32x32x16_bf16 v[38:53], v[200:203], v[10:13], 0
	v_mfma_f32_32x32x16_bf16 v[70:85], v[200:203], v[18:21], 0
	v_add_f32_e32 v219, v175, v176
	v_add_f32_e32 v220, v177, v178
	v_add_f32_e32 v211, v219, v220
	v_add_f32_e32 v219, v179, v180
	v_add_f32_e32 v220, v181, v182
	v_add_f32_e32 v212, v219, v220
	v_add_f32_e32 v219, v183, v184
	v_add_f32_e32 v220, v185, v186
	v_add_f32_e32 v213, v219, v220
	v_add_f32_e32 v219, v187, v188
	v_add_f32_e32 v220, v189, v190
	v_add_f32_e32 v214, v219, v220
	ds_bpermute_b32 v215, v208, v211
	ds_bpermute_b32 v216, v208, v212
	ds_bpermute_b32 v217, v208, v213
	ds_bpermute_b32 v218, v208, v214
	v_mul_f32_e32 v175, v86, v22
	v_mul_f32_e32 v179, v86, v54
	v_fma_f32 v175, -v102, v54, v175
	v_fmac_f32_e32 v179, v102, v22
	v_mul_f32_e32 v176, v87, v23
	v_mul_f32_e32 v180, v87, v55
	v_fma_f32 v176, -v103, v55, v176
	v_fmac_f32_e32 v180, v103, v23
	v_mul_f32_e32 v177, v88, v24
	v_mul_f32_e32 v181, v88, v56
	v_fma_f32 v177, -v104, v56, v177
	v_fmac_f32_e32 v181, v104, v24
	v_mul_f32_e32 v178, v89, v25
	v_mul_f32_e32 v182, v89, v57
	v_fma_f32 v178, -v105, v57, v178
	v_fmac_f32_e32 v182, v105, v25
	v_fmac_f32_e32 v175, v90, v26
	v_fmac_f32_e32 v179, v90, v58
	v_fma_f32 v175, -v106, v58, v175
	v_fmac_f32_e32 v179, v106, v26
	v_fmac_f32_e32 v176, v91, v27
	v_fmac_f32_e32 v180, v91, v59
	v_fma_f32 v176, -v107, v59, v176
	v_fmac_f32_e32 v180, v107, v27
	v_fmac_f32_e32 v177, v92, v28
	v_fmac_f32_e32 v181, v92, v60
	v_fma_f32 v177, -v108, v60, v177
	v_fmac_f32_e32 v181, v108, v28
	v_fmac_f32_e32 v178, v93, v29
	v_fmac_f32_e32 v182, v93, v61
	v_fma_f32 v178, -v109, v61, v178
	v_fmac_f32_e32 v182, v109, v29
	v_fmac_f32_e32 v175, v94, v30
	v_fmac_f32_e32 v179, v94, v62
	v_fma_f32 v175, -v110, v62, v175
	v_fmac_f32_e32 v179, v110, v30
	v_fmac_f32_e32 v176, v95, v31
	v_fmac_f32_e32 v180, v95, v63
	v_fma_f32 v176, -v111, v63, v176
	v_fmac_f32_e32 v180, v111, v31
	v_fmac_f32_e32 v177, v96, v32
	v_fmac_f32_e32 v181, v96, v64
	v_fma_f32 v177, -v112, v64, v177
	v_fmac_f32_e32 v181, v112, v32
	v_fmac_f32_e32 v178, v97, v33
	v_fmac_f32_e32 v182, v97, v65
	v_fma_f32 v178, -v113, v65, v178
	v_fmac_f32_e32 v182, v113, v33
	v_fmac_f32_e32 v175, v98, v34
	v_fmac_f32_e32 v179, v98, v66
	v_fma_f32 v175, -v114, v66, v175
	v_fmac_f32_e32 v179, v114, v34
	v_fmac_f32_e32 v176, v99, v35
	v_fmac_f32_e32 v180, v99, v67
	v_fma_f32 v176, -v115, v67, v176
	v_fmac_f32_e32 v180, v115, v35
	v_fmac_f32_e32 v177, v100, v36
	v_fmac_f32_e32 v181, v100, v68
	v_fma_f32 v177, -v116, v68, v177
	v_fmac_f32_e32 v181, v116, v36
	v_fmac_f32_e32 v178, v101, v37
	v_fmac_f32_e32 v182, v101, v69
	v_fma_f32 v178, -v117, v69, v178
	v_fmac_f32_e32 v182, v117, v37
	s_waitcnt lgkmcnt(0)
	v_add_f32_e32 v211, v211, v215
	v_add_f32_e32 v212, v212, v216
	v_add_f32_e32 v213, v213, v217
	v_add_f32_e32 v214, v214, v218
	v_fma_f32 v219, -v168, v172, v211
	v_fma_f32 v220, v168, v171, v212
	v_fma_f32 v171, v167, v171, v219
	v_fma_f32 v172, v167, v172, v220
	v_fma_f32 v219, -v170, v174, v213
	v_fma_f32 v220, v170, v173, v214
	v_fma_f32 v173, v169, v173, v219
	v_fma_f32 v174, v169, v174, v220
	v_mul_f32_e32 v183, v118, v38
	v_mul_f32_e32 v187, v118, v70
	v_fma_f32 v183, -v134, v70, v183
	v_fmac_f32_e32 v187, v134, v38
	v_mul_f32_e32 v184, v119, v39
	v_mul_f32_e32 v188, v119, v71
	v_fma_f32 v184, -v135, v71, v184
	v_fmac_f32_e32 v188, v135, v39
	v_mul_f32_e32 v185, v120, v40
	v_mul_f32_e32 v189, v120, v72
	v_fma_f32 v185, -v136, v72, v185
	v_fmac_f32_e32 v189, v136, v40
	v_mul_f32_e32 v186, v121, v41
	v_mul_f32_e32 v190, v121, v73
	v_fma_f32 v186, -v137, v73, v186
	v_fmac_f32_e32 v190, v137, v41
	v_fmac_f32_e32 v183, v122, v42
	v_fmac_f32_e32 v187, v122, v74
	v_fma_f32 v183, -v138, v74, v183
	v_fmac_f32_e32 v187, v138, v42
	v_fmac_f32_e32 v184, v123, v43
	v_fmac_f32_e32 v188, v123, v75
	v_fma_f32 v184, -v139, v75, v184
	v_fmac_f32_e32 v188, v139, v43
	v_fmac_f32_e32 v185, v124, v44
	v_fmac_f32_e32 v189, v124, v76
	v_fma_f32 v185, -v140, v76, v185
	v_fmac_f32_e32 v189, v140, v44
	v_fmac_f32_e32 v186, v125, v45
	v_fmac_f32_e32 v190, v125, v77
	v_fma_f32 v186, -v141, v77, v186
	v_fmac_f32_e32 v190, v141, v45
	v_fmac_f32_e32 v183, v126, v46
	v_fmac_f32_e32 v187, v126, v78
	v_fma_f32 v183, -v142, v78, v183
	v_fmac_f32_e32 v187, v142, v46
	v_fmac_f32_e32 v184, v127, v47
	v_fmac_f32_e32 v188, v127, v79
	v_fma_f32 v184, -v143, v79, v184
	v_fmac_f32_e32 v188, v143, v47
	v_fmac_f32_e32 v185, v128, v48
	v_fmac_f32_e32 v189, v128, v80
	v_fma_f32 v185, -v144, v80, v185
	v_fmac_f32_e32 v189, v144, v48
	v_fmac_f32_e32 v186, v129, v49
	v_fmac_f32_e32 v190, v129, v81
	v_fma_f32 v186, -v145, v81, v186
	v_fmac_f32_e32 v190, v145, v49
	v_fmac_f32_e32 v183, v130, v50
	v_fmac_f32_e32 v187, v130, v82
	v_fma_f32 v183, -v146, v82, v183
	v_fmac_f32_e32 v187, v146, v50
	v_fmac_f32_e32 v184, v131, v51
	v_fmac_f32_e32 v188, v131, v83
	v_fma_f32 v184, -v147, v83, v184
	v_fmac_f32_e32 v188, v147, v51
	v_fmac_f32_e32 v185, v132, v52
	v_fmac_f32_e32 v189, v132, v84
	v_fma_f32 v185, -v148, v84, v185
	v_fmac_f32_e32 v189, v148, v52
	v_fmac_f32_e32 v186, v133, v53
	v_fmac_f32_e32 v190, v133, v85
	v_fma_f32 v186, -v149, v85, v186
	v_fmac_f32_e32 v190, v149, v53
	s_waitcnt vmcnt(4)
	v_mfma_f32_32x32x16_bf16 v[22:37], v[204:207], v[6:9], 0
	v_mfma_f32_32x32x16_bf16 v[54:69], v[204:207], v[14:17], 0
	v_mfma_f32_32x32x16_bf16 v[38:53], v[204:207], v[10:13], 0
	v_mfma_f32_32x32x16_bf16 v[70:85], v[204:207], v[18:21], 0
	v_add_f32_e32 v219, v175, v176
	v_add_f32_e32 v220, v177, v178
	v_add_f32_e32 v211, v219, v220
	v_add_f32_e32 v219, v179, v180
	v_add_f32_e32 v220, v181, v182
	v_add_f32_e32 v212, v219, v220
	v_add_f32_e32 v219, v183, v184
	v_add_f32_e32 v220, v185, v186
	v_add_f32_e32 v213, v219, v220
	v_add_f32_e32 v219, v187, v188
	v_add_f32_e32 v220, v189, v190
	v_add_f32_e32 v214, v219, v220
	ds_bpermute_b32 v215, v208, v211
	ds_bpermute_b32 v216, v208, v212
	ds_bpermute_b32 v217, v208, v213
	ds_bpermute_b32 v218, v208, v214
	v_mul_f32_e32 v175, v86, v22
	v_mul_f32_e32 v179, v86, v54
	v_fma_f32 v175, -v102, v54, v175
	v_fmac_f32_e32 v179, v102, v22
	v_mul_f32_e32 v176, v87, v23
	v_mul_f32_e32 v180, v87, v55
	v_fma_f32 v176, -v103, v55, v176
	v_fmac_f32_e32 v180, v103, v23
	v_mul_f32_e32 v177, v88, v24
	v_mul_f32_e32 v181, v88, v56
	v_fma_f32 v177, -v104, v56, v177
	v_fmac_f32_e32 v181, v104, v24
	v_mul_f32_e32 v178, v89, v25
	v_mul_f32_e32 v182, v89, v57
	v_fma_f32 v178, -v105, v57, v178
	v_fmac_f32_e32 v182, v105, v25
	v_fmac_f32_e32 v175, v90, v26
	v_fmac_f32_e32 v179, v90, v58
	v_fma_f32 v175, -v106, v58, v175
	v_fmac_f32_e32 v179, v106, v26
	v_fmac_f32_e32 v176, v91, v27
	v_fmac_f32_e32 v180, v91, v59
	v_fma_f32 v176, -v107, v59, v176
	v_fmac_f32_e32 v180, v107, v27
	v_fmac_f32_e32 v177, v92, v28
	v_fmac_f32_e32 v181, v92, v60
	v_fma_f32 v177, -v108, v60, v177
	v_fmac_f32_e32 v181, v108, v28
	v_fmac_f32_e32 v178, v93, v29
	v_fmac_f32_e32 v182, v93, v61
	v_fma_f32 v178, -v109, v61, v178
	v_fmac_f32_e32 v182, v109, v29
	v_fmac_f32_e32 v175, v94, v30
	v_fmac_f32_e32 v179, v94, v62
	v_fma_f32 v175, -v110, v62, v175
	v_fmac_f32_e32 v179, v110, v30
	v_fmac_f32_e32 v176, v95, v31
	v_fmac_f32_e32 v180, v95, v63
	v_fma_f32 v176, -v111, v63, v176
	v_fmac_f32_e32 v180, v111, v31
	v_fmac_f32_e32 v177, v96, v32
	v_fmac_f32_e32 v181, v96, v64
	v_fma_f32 v177, -v112, v64, v177
	v_fmac_f32_e32 v181, v112, v32
	v_fmac_f32_e32 v178, v97, v33
	v_fmac_f32_e32 v182, v97, v65
	v_fma_f32 v178, -v113, v65, v178
	v_fmac_f32_e32 v182, v113, v33
	v_fmac_f32_e32 v175, v98, v34
	v_fmac_f32_e32 v179, v98, v66
	v_fma_f32 v175, -v114, v66, v175
	v_fmac_f32_e32 v179, v114, v34
	v_fmac_f32_e32 v176, v99, v35
	v_fmac_f32_e32 v180, v99, v67
	v_fma_f32 v176, -v115, v67, v176
	v_fmac_f32_e32 v180, v115, v35
	v_fmac_f32_e32 v177, v100, v36
	v_fmac_f32_e32 v181, v100, v68
	v_fma_f32 v177, -v116, v68, v177
	v_fmac_f32_e32 v181, v116, v36
	v_fmac_f32_e32 v178, v101, v37
	v_fmac_f32_e32 v182, v101, v69
	v_fma_f32 v178, -v117, v69, v178
	v_fmac_f32_e32 v182, v117, v37
	s_waitcnt lgkmcnt(0)
	v_add_f32_e32 v211, v211, v215
	v_add_f32_e32 v212, v212, v216
	v_add_f32_e32 v213, v213, v217
	v_add_f32_e32 v214, v214, v218
	v_fma_f32 v219, -v168, v172, v211
	v_fma_f32 v220, v168, v171, v212
	v_fma_f32 v171, v167, v171, v219
	v_fma_f32 v172, v167, v172, v220
	v_fma_f32 v219, -v170, v174, v213
	v_fma_f32 v220, v170, v173, v214
	v_fma_f32 v173, v169, v173, v219
	v_fma_f32 v174, v169, v174, v220
	v_mul_f32_e32 v183, v118, v38
	v_mul_f32_e32 v187, v118, v70
	v_fma_f32 v183, -v134, v70, v183
	v_fmac_f32_e32 v187, v134, v38
	v_mul_f32_e32 v184, v119, v39
	v_mul_f32_e32 v188, v119, v71
	v_fma_f32 v184, -v135, v71, v184
	v_fmac_f32_e32 v188, v135, v39
	v_mul_f32_e32 v185, v120, v40
	v_mul_f32_e32 v189, v120, v72
	v_fma_f32 v185, -v136, v72, v185
	v_fmac_f32_e32 v189, v136, v40
	v_mul_f32_e32 v186, v121, v41
	v_mul_f32_e32 v190, v121, v73
	v_fma_f32 v186, -v137, v73, v186
	v_fmac_f32_e32 v190, v137, v41
	v_fmac_f32_e32 v183, v122, v42
	v_fmac_f32_e32 v187, v122, v74
	v_fma_f32 v183, -v138, v74, v183
	v_fmac_f32_e32 v187, v138, v42
	v_fmac_f32_e32 v184, v123, v43
	v_fmac_f32_e32 v188, v123, v75
	v_fma_f32 v184, -v139, v75, v184
	v_fmac_f32_e32 v188, v139, v43
	v_fmac_f32_e32 v185, v124, v44
	v_fmac_f32_e32 v189, v124, v76
	v_fma_f32 v185, -v140, v76, v185
	v_fmac_f32_e32 v189, v140, v44
	v_fmac_f32_e32 v186, v125, v45
	v_fmac_f32_e32 v190, v125, v77
	v_fma_f32 v186, -v141, v77, v186
	v_fmac_f32_e32 v190, v141, v45
	v_fmac_f32_e32 v183, v126, v46
	v_fmac_f32_e32 v187, v126, v78
	v_fma_f32 v183, -v142, v78, v183
	v_fmac_f32_e32 v187, v142, v46
	v_fmac_f32_e32 v184, v127, v47
	v_fmac_f32_e32 v188, v127, v79
	v_fma_f32 v184, -v143, v79, v184
	v_fmac_f32_e32 v188, v143, v47
	v_fmac_f32_e32 v185, v128, v48
	v_fmac_f32_e32 v189, v128, v80
	v_fma_f32 v185, -v144, v80, v185
	v_fmac_f32_e32 v189, v144, v48
	v_fmac_f32_e32 v186, v129, v49
	v_fmac_f32_e32 v190, v129, v81
	v_fma_f32 v186, -v145, v81, v186
	v_fmac_f32_e32 v190, v145, v49
	v_fmac_f32_e32 v183, v130, v50
	v_fmac_f32_e32 v187, v130, v82
	v_fma_f32 v183, -v146, v82, v183
	v_fmac_f32_e32 v187, v146, v50
	v_fmac_f32_e32 v184, v131, v51
	v_fmac_f32_e32 v188, v131, v83
	v_fma_f32 v184, -v147, v83, v184
	v_fmac_f32_e32 v188, v147, v51
	v_fmac_f32_e32 v185, v132, v52
	v_fmac_f32_e32 v189, v132, v84
	v_fma_f32 v185, -v148, v84, v185
	v_fmac_f32_e32 v189, v148, v52
	v_fmac_f32_e32 v186, v133, v53
	v_fmac_f32_e32 v190, v133, v85
	v_fma_f32 v186, -v149, v85, v186
	v_fmac_f32_e32 v190, v149, v53
	v_add_f32_e32 v219, v175, v176
	v_add_f32_e32 v220, v177, v178
	v_add_f32_e32 v211, v219, v220
	v_add_f32_e32 v219, v179, v180
	v_add_f32_e32 v220, v181, v182
	v_add_f32_e32 v212, v219, v220
	v_add_f32_e32 v219, v183, v184
	v_add_f32_e32 v220, v185, v186
	v_add_f32_e32 v213, v219, v220
	v_add_f32_e32 v219, v187, v188
	v_add_f32_e32 v220, v189, v190
	v_add_f32_e32 v214, v219, v220
	ds_bpermute_b32 v215, v208, v211
	ds_bpermute_b32 v216, v208, v212
	ds_bpermute_b32 v217, v208, v213
	ds_bpermute_b32 v218, v208, v214
	s_waitcnt lgkmcnt(0)
	v_add_f32_e32 v211, v211, v215
	v_add_f32_e32 v212, v212, v216
	v_add_f32_e32 v213, v213, v217
	v_add_f32_e32 v214, v214, v218
	v_fma_f32 v219, -v168, v172, v211
	v_fma_f32 v220, v168, v171, v212
	v_fma_f32 v171, v167, v171, v219
	v_fma_f32 v172, v167, v172, v220
	v_fma_f32 v219, -v170, v174, v213
	v_fma_f32 v220, v170, v173, v214
	v_fma_f32 v173, v169, v173, v219
	v_fma_f32 v174, v169, v174, v220
	s_add_u32 s42, s38, 0x600
	s_addc_u32 s43, s39, 0
	s_mov_b64 exec, s[12:13]
	global_store_dword v209, v171, s[42:43]
	global_store_dword v209, v172, s[42:43] offset:256
	global_store_dword v209, v173, s[42:43] offset:128
	global_store_dword v209, v174, s[42:43] offset:384
	s_mov_b64 exec, -1
	s_branch .LBB0_1315
.Lpa_compiled:
	v_and_b32_e32 v3, 63, v2
	v_lshlrev_b32_e32 v70, 4, v3
	v_mov_b32_e32 v71, 0
	s_ashr_i32 s12, s0, 6
	v_lshl_add_u64 v[4:5], s[54:55], 0, v[70:71]
	s_mov_b64 s[0:1], 0x140000
	v_lshl_add_u64 v[72:73], v[4:5], 0, s[0:1]
	v_mbcnt_hi_u32_b32 v4, -1, v1
	v_and_b32_e32 v6, 64, v4
	v_xor_b32_e32 v5, 32, v4
	v_add_u32_e32 v6, 64, v6
	v_and_b32_e32 v68, 31, v2
	v_cmp_lt_i32_e64 s[6:7], v5, v6
	v_lshrrev_b32_e32 v2, 2, v2
	v_lshlrev_b32_e32 v70, 2, v68
	v_cndmask_b32_e64 v4, v4, v5, s[6:7]
	v_and_b32_e32 v2, 8, v2
	v_lshlrev_b32_e32 v69, 2, v4
	v_cmp_lt_u32_e64 s[6:7], 31, v3
	v_lshl_add_u64 v[4:5], s[54:55], 0, v[70:71]
	s_mov_b64 s[0:1], 0x600000
	v_cmp_gt_u32_e32 vcc, 32, v3
	s_mov_b32 s9, 0
	v_lshl_add_u64 v[74:75], v[4:5], 0, s[0:1]
	v_lshlrev_b32_e32 v165, 1, v68
	v_lshlrev_b32_e32 v70, 1, v2
	s_xor_b64 s[6:7], s[6:7], -1
	v_readlane_b32 s13, v255, 7
	s_branch .LBB0_1311
